# nt loads for P0 read-once inputs + deeper-prefetch x/p conversion path + nt stores for PP (read only in P6) on top of LDS-transposed coalesced epilogue stores
# speedup vs baseline: 1.0385x; 1.0331x over previous
.LBB0_21:
	s_cmpk_gt_i32 s94, 0x37f
	s_mov_b64 s[4:5], -1
	s_cbranch_scc0 .LBB0_115
	s_cmpk_gt_u32 s94, 0x57f
	s_cbranch_scc0 .LBB0_84
	s_cmpk_gt_u32 s94, 0x107f
	s_cbranch_scc0 .LBB0_57
	s_cmpk_gt_u32 s94, 0x15ff
	s_cbranch_scc0 .LBB0_54
	s_cmpk_gt_u32 s94, 0x17ff
	s_cbranch_scc0 .LBB0_27
	s_load_dwordx2 s[8:9], s[0:1], 0x98
	s_and_b32 s4, s7, 0x3e0
	s_and_b32 s5, s21, 0x1c0
	s_lshl_b32 s10, s4, 2
	v_or_b32_e32 v18, s5, v0
	s_waitcnt lgkmcnt(0)
	s_add_u32 s8, s8, s10
	s_addc_u32 s9, s9, 0
	v_lshl_add_u64 v[16:17], s[8:9], 0, v[2:3]
	v_lshlrev_b32_e32 v18, 12, v18
	v_mov_b32_e32 v19, v3
	v_lshl_add_u64 v[16:17], v[16:17], 0, v[18:19]
	v_add_co_u32_e32 v18, vcc, s23, v16
	s_lshl_b32 s14, s5, 1
	s_nop 0
	v_addc_co_u32_e32 v19, vcc, 0, v17, vcc
	v_add_co_u32_e32 v20, vcc, s24, v16
	s_nop 1
	v_addc_co_u32_e32 v21, vcc, 0, v17, vcc
	v_add_co_u32_e32 v22, vcc, s25, v16
	s_nop 1
	v_addc_co_u32_e32 v23, vcc, 0, v17, vcc
	v_add_co_u32_e32 v24, vcc, s31, v16
	s_nop 1
	v_addc_co_u32_e32 v25, vcc, 0, v17, vcc
	v_add_co_u32_e32 v26, vcc, s36, v16
	s_nop 1
	v_addc_co_u32_e32 v27, vcc, 0, v17, vcc
	v_add_co_u32_e32 v28, vcc, s37, v16
	s_nop 1
	v_addc_co_u32_e32 v29, vcc, 0, v17, vcc
	v_add_co_u32_e32 v30, vcc, s38, v16
	s_nop 1
	v_addc_co_u32_e32 v31, vcc, 0, v17, vcc
	global_load_dword v61, v[16:17], off nt
	global_load_dword v62, v[18:19], off nt
	global_load_dword v63, v[20:21], off nt
	global_load_dword v64, v[22:23], off nt
	global_load_dword v65, v[24:25], off nt
	global_load_dword v66, v[26:27], off nt
	global_load_dword v67, v[28:29], off nt
	global_load_dword v68, v[30:31], off nt
	v_add_co_u32_e32 v18, vcc, s39, v16
	s_nop 1
	v_addc_co_u32_e32 v19, vcc, 0, v17, vcc
	v_add_co_u32_e32 v20, vcc, s40, v16
	s_nop 1
	v_addc_co_u32_e32 v21, vcc, 0, v17, vcc
	v_add_co_u32_e32 v22, vcc, s41, v16
	s_nop 1
	v_addc_co_u32_e32 v23, vcc, 0, v17, vcc
	v_add_co_u32_e32 v24, vcc, s42, v16
	s_nop 1
	v_addc_co_u32_e32 v25, vcc, 0, v17, vcc
	v_add_co_u32_e32 v26, vcc, s43, v16
	s_nop 1
	v_addc_co_u32_e32 v27, vcc, 0, v17, vcc
	v_add_co_u32_e32 v28, vcc, s44, v16
	s_nop 1
	v_addc_co_u32_e32 v29, vcc, 0, v17, vcc
	v_add_co_u32_e32 v30, vcc, s45, v16
	s_nop 1
	v_addc_co_u32_e32 v31, vcc, 0, v17, vcc
	v_add_co_u32_e32 v32, vcc, s46, v16
	s_nop 1
	v_addc_co_u32_e32 v33, vcc, 0, v17, vcc
	global_load_dword v69, v[18:19], off nt
	global_load_dword v70, v[20:21], off nt
	global_load_dword v71, v[22:23], off nt
	global_load_dword v72, v[24:25], off nt
	global_load_dword v73, v[26:27], off nt
	global_load_dword v74, v[28:29], off nt
	global_load_dword v75, v[30:31], off nt
	global_load_dword v76, v[32:33], off nt
	v_add_co_u32_e32 v18, vcc, s47, v16
	s_nop 1
	v_addc_co_u32_e32 v19, vcc, 0, v17, vcc
	v_add_co_u32_e32 v20, vcc, s48, v16
	s_nop 1
	v_addc_co_u32_e32 v21, vcc, 0, v17, vcc
	v_add_co_u32_e32 v22, vcc, s49, v16
	s_nop 1
	v_addc_co_u32_e32 v23, vcc, 0, v17, vcc
	v_add_co_u32_e32 v24, vcc, s50, v16
	s_nop 1
	v_addc_co_u32_e32 v25, vcc, 0, v17, vcc
	v_add_co_u32_e32 v26, vcc, s51, v16
	s_nop 1
	v_addc_co_u32_e32 v27, vcc, 0, v17, vcc
	v_add_co_u32_e32 v28, vcc, s52, v16
	s_nop 1
	v_addc_co_u32_e32 v29, vcc, 0, v17, vcc
	v_add_co_u32_e32 v30, vcc, s53, v16
	s_nop 1
	v_addc_co_u32_e32 v31, vcc, 0, v17, vcc
	v_add_co_u32_e32 v32, vcc, s54, v16
	s_nop 1
	v_addc_co_u32_e32 v33, vcc, 0, v17, vcc
	global_load_dword v77, v[18:19], off nt
	global_load_dword v78, v[20:21], off nt
	global_load_dword v79, v[22:23], off nt
	global_load_dword v80, v[24:25], off nt
	global_load_dword v81, v[26:27], off nt
	global_load_dword v82, v[28:29], off nt
	global_load_dword v83, v[30:31], off nt
	s_nop 0
	global_load_dword v32, v[32:33], off nt
	v_add_co_u32_e32 v18, vcc, s55, v16
	s_nop 1
	v_addc_co_u32_e32 v19, vcc, 0, v17, vcc
	v_add_co_u32_e32 v20, vcc, s57, v16
	s_nop 1
	v_addc_co_u32_e32 v21, vcc, 0, v17, vcc
	v_add_co_u32_e32 v22, vcc, s58, v16
	s_nop 1
	v_addc_co_u32_e32 v23, vcc, 0, v17, vcc
	v_add_co_u32_e32 v24, vcc, s59, v16
	s_nop 1
	v_addc_co_u32_e32 v25, vcc, 0, v17, vcc
	v_add_co_u32_e32 v26, vcc, s60, v16
	s_nop 1
	v_addc_co_u32_e32 v27, vcc, 0, v17, vcc
	v_add_co_u32_e32 v28, vcc, s61, v16
	s_nop 1
	v_addc_co_u32_e32 v29, vcc, 0, v17, vcc
	v_add_co_u32_e32 v30, vcc, s62, v16
	s_nop 1
	v_addc_co_u32_e32 v31, vcc, 0, v17, vcc
	v_add_co_u32_e32 v16, vcc, s63, v16
	s_nop 1
	v_addc_co_u32_e32 v17, vcc, 0, v17, vcc
	global_load_dword v18, v[18:19], off nt
	s_nop 0
	global_load_dword v19, v[20:21], off nt
	s_nop 0
	global_load_dword v20, v[22:23], off nt
	global_load_dword v21, v[24:25], off nt
	s_nop 0
	global_load_dword v22, v[26:27], off nt
	global_load_dword v23, v[28:29], off nt
	global_load_dword v24, v[30:31], off nt
	s_nop 0
	global_load_dword v16, v[16:17], off nt
	s_waitcnt vmcnt(30)
	ds_write2_b32 v35, v61, v62 offset1:66
	s_waitcnt vmcnt(28)
	ds_write2_b32 v35, v63, v64 offset0:132 offset1:198
	s_waitcnt vmcnt(26)
	ds_write2_b32 v54, v65, v66 offset0:8 offset1:74
	s_waitcnt vmcnt(24)
	ds_write2_b32 v54, v67, v68 offset0:140 offset1:206
	s_waitcnt vmcnt(22)
	ds_write2_b32 v55, v69, v70 offset0:16 offset1:82
	s_waitcnt vmcnt(20)
	ds_write2_b32 v55, v71, v72 offset0:148 offset1:214
	s_waitcnt vmcnt(18)
	ds_write2_b32 v56, v73, v74 offset0:24 offset1:90
	s_waitcnt vmcnt(16)
	ds_write2_b32 v56, v75, v76 offset0:156 offset1:222
	s_waitcnt vmcnt(14)
	ds_write2_b32 v57, v77, v78 offset0:32 offset1:98
	s_waitcnt vmcnt(12)
	ds_write2_b32 v57, v79, v80 offset0:164 offset1:230
	s_waitcnt vmcnt(10)
	ds_write2_b32 v58, v81, v82 offset0:40 offset1:106
	s_waitcnt vmcnt(8)
	ds_write2_b32 v58, v83, v32 offset0:172 offset1:238
	s_waitcnt vmcnt(6)
	ds_write2_b32 v59, v18, v19 offset0:48 offset1:114
	s_waitcnt vmcnt(4)
	ds_write2_b32 v59, v20, v21 offset0:180 offset1:246
	s_waitcnt vmcnt(2)
	ds_write2_b32 v60, v22, v23 offset0:56 offset1:122
	s_waitcnt vmcnt(0)
	ds_write2_b32 v60, v24, v16 offset0:188 offset1:254
	s_waitcnt lgkmcnt(0)
	ds_read2_b32 v[20:21], v37 offset1:8
	ds_read2_b32 v[24:25], v37 offset0:33 offset1:41
	ds_read2_b32 v[26:27], v37 offset0:66 offset1:74
	ds_read2_b32 v[28:29], v37 offset0:99 offset1:107
	ds_read2_b32 v[30:31], v37 offset0:132 offset1:140
	s_waitcnt lgkmcnt(4)
	v_bfe_u32 v16, v20, 16, 1
	v_add3_u32 v16, v20, v16, s64
	s_waitcnt lgkmcnt(3)
	v_bfe_u32 v17, v24, 16, 1
	v_lshrrev_b32_e32 v16, 16, v16
	v_add3_u32 v17, v24, v17, s64
	ds_read2_b32 v[32:33], v37 offset0:165 offset1:173
	v_and_or_b32 v16, v17, s65, v16
	s_waitcnt lgkmcnt(3)
	v_bfe_u32 v17, v26, 16, 1
	v_add3_u32 v17, v26, v17, s64
	s_waitcnt lgkmcnt(2)
	v_bfe_u32 v18, v28, 16, 1
	ds_read2_b32 v[62:63], v37 offset0:198 offset1:206
	v_lshrrev_b32_e32 v17, 16, v17
	v_add3_u32 v18, v28, v18, s64
	ds_read2_b32 v[64:65], v37 offset0:231 offset1:239
	v_and_or_b32 v17, v18, s65, v17
	s_waitcnt lgkmcnt(3)
	v_bfe_u32 v18, v30, 16, 1
	v_add3_u32 v18, v30, v18, s64
	s_waitcnt lgkmcnt(2)
	v_bfe_u32 v19, v32, 16, 1
	v_lshrrev_b32_e32 v18, 16, v18
	v_add3_u32 v19, v32, v19, s64
	v_and_or_b32 v18, v19, s65, v18
	s_waitcnt lgkmcnt(1)
	v_bfe_u32 v19, v62, 16, 1
	v_add3_u32 v19, v62, v19, s64
	s_waitcnt lgkmcnt(0)
	v_bfe_u32 v20, v64, 16, 1
	v_lshrrev_b32_e32 v19, 16, v19
	v_add3_u32 v20, v64, v20, s64
	v_and_or_b32 v19, v20, s65, v19
	v_or_b32_e32 v20, s4, v36
	v_lshl_add_u64 v[22:23], v[6:7], 0, s[14:15]
	v_lshlrev_b32_e32 v66, 9, v20
	v_mov_b32_e32 v67, v3
	v_lshl_add_u64 v[66:67], v[22:23], 0, v[66:67]
	global_store_dwordx4 v[66:67], v[16:19], off
	v_bfe_u32 v20, v65, 16, 1
	v_add3_u32 v20, v65, v20, s64
	v_bfe_u32 v16, v21, 16, 1
	v_add3_u32 v16, v21, v16, s64
	v_bfe_u32 v17, v25, 16, 1
	v_lshrrev_b32_e32 v16, 16, v16
	v_add3_u32 v17, v25, v17, s64
	v_and_or_b32 v16, v17, s65, v16
	v_bfe_u32 v17, v27, 16, 1
	v_add3_u32 v17, v27, v17, s64
	v_bfe_u32 v18, v29, 16, 1
	v_lshrrev_b32_e32 v17, 16, v17
	v_add3_u32 v18, v29, v18, s64
	v_and_or_b32 v17, v18, s65, v17
	v_bfe_u32 v18, v31, 16, 1
	v_add3_u32 v18, v31, v18, s64
	v_bfe_u32 v19, v33, 16, 1
	v_lshrrev_b32_e32 v18, 16, v18
	v_add3_u32 v19, v33, v19, s64
	v_and_or_b32 v18, v19, s65, v18
	v_bfe_u32 v19, v63, 16, 1
	v_add3_u32 v19, v63, v19, s64
	v_lshrrev_b32_e32 v19, 16, v19
	v_and_or_b32 v19, v20, s65, v19
	v_or_b32_e32 v20, s4, v38
	v_lshlrev_b32_e32 v20, 9, v20
	v_mov_b32_e32 v21, v3
	ds_read2_b32 v[24:25], v37 offset0:16 offset1:24
	v_lshl_add_u64 v[20:21], v[22:23], 0, v[20:21]
	global_store_dwordx4 v[20:21], v[16:19], off
	ds_read2_b32 v[20:21], v37 offset0:49 offset1:57
	ds_read2_b32 v[26:27], v37 offset0:82 offset1:90
	ds_read2_b32 v[28:29], v37 offset0:115 offset1:123
	s_waitcnt lgkmcnt(3)
	v_bfe_u32 v16, v24, 16, 1
	v_add3_u32 v16, v24, v16, s64
	s_waitcnt lgkmcnt(2)
	v_bfe_u32 v17, v20, 16, 1
	ds_read2_b32 v[30:31], v37 offset0:148 offset1:156
	v_lshrrev_b32_e32 v16, 16, v16
	v_add3_u32 v17, v20, v17, s64
	ds_read2_b32 v[32:33], v37 offset0:181 offset1:189
	v_and_or_b32 v16, v17, s65, v16
	s_waitcnt lgkmcnt(3)
	v_bfe_u32 v17, v26, 16, 1
	v_add3_u32 v17, v26, v17, s64
	s_waitcnt lgkmcnt(2)
	v_bfe_u32 v18, v28, 16, 1
	ds_read2_b32 v[62:63], v37 offset0:214 offset1:222
	v_lshrrev_b32_e32 v17, 16, v17
	v_add3_u32 v18, v28, v18, s64
	ds_read2_b32 v[64:65], v37 offset0:247 offset1:255
	v_and_or_b32 v17, v18, s65, v17
	s_waitcnt lgkmcnt(3)
	v_bfe_u32 v18, v30, 16, 1
	v_add3_u32 v18, v30, v18, s64
	s_waitcnt lgkmcnt(2)
	v_bfe_u32 v19, v32, 16, 1
	v_lshrrev_b32_e32 v18, 16, v18
	v_add3_u32 v19, v32, v19, s64
	v_and_or_b32 v18, v19, s65, v18
	s_waitcnt lgkmcnt(1)
	v_bfe_u32 v19, v62, 16, 1
	v_add3_u32 v19, v62, v19, s64
	s_waitcnt lgkmcnt(0)
	v_bfe_u32 v20, v64, 16, 1
	v_lshrrev_b32_e32 v19, 16, v19
	v_add3_u32 v20, v64, v20, s64
	v_and_or_b32 v19, v20, s65, v19
	v_or_b32_e32 v20, s4, v39
	v_lshlrev_b32_e32 v66, 9, v20
	v_mov_b32_e32 v67, v3
	v_lshl_add_u64 v[66:67], v[22:23], 0, v[66:67]
	global_store_dwordx4 v[66:67], v[16:19], off
	v_or_b32_e32 v20, s4, v40
	v_lshlrev_b32_e32 v20, 9, v20
	v_bfe_u32 v17, v25, 16, 1
	v_bfe_u32 v16, v21, 16, 1
	v_add3_u32 v17, v25, v17, s64
	v_add3_u32 v16, v21, v16, s64
	v_lshrrev_b32_e32 v17, 16, v17
	v_bfe_u32 v18, v27, 16, 1
	v_and_or_b32 v16, v16, s65, v17
	v_bfe_u32 v17, v29, 16, 1
	v_add3_u32 v18, v27, v18, s64
	v_add3_u32 v17, v29, v17, s64
	v_lshrrev_b32_e32 v18, 16, v18
	v_bfe_u32 v19, v31, 16, 1
	v_and_or_b32 v17, v17, s65, v18
	v_bfe_u32 v18, v33, 16, 1
	v_add3_u32 v19, v31, v19, s64
	v_add3_u32 v18, v33, v18, s64
	v_lshrrev_b32_e32 v19, 16, v19
	v_bfe_u32 v21, v63, 16, 1
	v_and_or_b32 v18, v18, s65, v19
	v_bfe_u32 v19, v65, 16, 1
	v_add3_u32 v21, v63, v21, s64
	v_add3_u32 v19, v65, v19, s64
	v_lshrrev_b32_e32 v21, 16, v21
	v_and_or_b32 v19, v19, s65, v21
	v_mov_b32_e32 v21, v3
	v_lshl_add_u64 v[20:21], v[22:23], 0, v[20:21]
	global_store_dwordx4 v[20:21], v[16:19], off
	s_waitcnt lgkmcnt(0)
	s_mov_b64 s[4:5], 0
.LBB0_27:
	s_andn2_b64 vcc, exec, s[4:5]
	s_cbranch_vccnz .LBB0_53
	s_load_dwordx4 s[8:11], s[0:1], 0x88
	s_add_i32 s4, s21, 0x1d400
	s_and_b32 s16, s7, 0x3e0
	s_and_b32 s14, s4, 0x1ffc0
	s_lshl_b32 s4, s16, 2
	s_waitcnt lgkmcnt(0)
	s_add_u32 s4, s10, s4
	v_or_b32_e32 v32, s14, v0
	s_addc_u32 s5, s11, 0
	v_lshl_add_u64 v[16:17], s[4:5], 0, v[2:3]
	v_lshlrev_b32_e32 v18, 12, v32
	v_mov_b32_e32 v19, v3
	v_lshl_add_u64 v[16:17], v[16:17], 0, v[18:19]
	v_add_co_u32_e32 v18, vcc, s23, v16
	s_cmp_lg_u64 s[8:9], 0
	s_nop 0
	v_addc_co_u32_e32 v19, vcc, 0, v17, vcc
	v_add_co_u32_e32 v20, vcc, s24, v16
	s_cselect_b64 s[10:11], -1, 0
	s_nop 0
	v_addc_co_u32_e32 v21, vcc, 0, v17, vcc
	v_add_co_u32_e32 v22, vcc, s25, v16
	s_cmp_eq_u64 s[8:9], 0
	s_nop 0
	v_addc_co_u32_e32 v23, vcc, 0, v17, vcc
	v_add_co_u32_e32 v24, vcc, s31, v16
	s_nop 1
	v_addc_co_u32_e32 v25, vcc, 0, v17, vcc
	v_add_co_u32_e32 v26, vcc, s36, v16
	s_nop 1
	v_addc_co_u32_e32 v27, vcc, 0, v17, vcc
	v_add_co_u32_e32 v28, vcc, s37, v16
	s_nop 1
	v_addc_co_u32_e32 v29, vcc, 0, v17, vcc
	v_add_co_u32_e32 v62, vcc, s38, v16
	s_nop 1
	v_addc_co_u32_e32 v63, vcc, 0, v17, vcc
	global_load_dword v77, v[16:17], off nt
	global_load_dword v76, v[18:19], off nt
	global_load_dword v30, v[20:21], off nt
	global_load_dword v31, v[22:23], off nt
	global_load_dword v74, v[24:25], off nt
	global_load_dword v75, v[26:27], off nt
	s_nop 0
	global_load_dword v28, v[28:29], off nt
	s_nop 0
	global_load_dword v29, v[62:63], off nt
	v_add_co_u32_e32 v18, vcc, s39, v16
	s_nop 1
	v_addc_co_u32_e32 v19, vcc, 0, v17, vcc
	v_add_co_u32_e32 v20, vcc, s40, v16
	s_nop 1
	v_addc_co_u32_e32 v21, vcc, 0, v17, vcc
	v_add_co_u32_e32 v22, vcc, s41, v16
	s_nop 1
	v_addc_co_u32_e32 v23, vcc, 0, v17, vcc
	v_add_co_u32_e32 v24, vcc, s42, v16
	s_nop 1
	v_addc_co_u32_e32 v25, vcc, 0, v17, vcc
	v_add_co_u32_e32 v62, vcc, s43, v16
	s_nop 1
	v_addc_co_u32_e32 v63, vcc, 0, v17, vcc
	v_add_co_u32_e32 v64, vcc, s44, v16
	s_nop 1
	v_addc_co_u32_e32 v65, vcc, 0, v17, vcc
	v_add_co_u32_e32 v66, vcc, s45, v16
	s_nop 1
	v_addc_co_u32_e32 v67, vcc, 0, v17, vcc
	v_add_co_u32_e32 v68, vcc, s46, v16
	s_nop 1
	v_addc_co_u32_e32 v69, vcc, 0, v17, vcc
	global_load_dword v72, v[18:19], off nt
	global_load_dword v73, v[20:21], off nt
	global_load_dword v26, v[22:23], off nt
	global_load_dword v27, v[24:25], off nt
	global_load_dword v70, v[62:63], off nt
	global_load_dword v71, v[64:65], off nt
	s_nop 0
	global_load_dword v24, v[66:67], off nt
	global_load_dword v25, v[68:69], off nt
	v_add_co_u32_e32 v18, vcc, s47, v16
	s_nop 1
	v_addc_co_u32_e32 v19, vcc, 0, v17, vcc
	v_add_co_u32_e32 v20, vcc, s48, v16
	s_nop 1
	v_addc_co_u32_e32 v21, vcc, 0, v17, vcc
	v_add_co_u32_e32 v22, vcc, s49, v16
	s_nop 1
	v_addc_co_u32_e32 v23, vcc, 0, v17, vcc
	v_add_co_u32_e32 v62, vcc, s50, v16
	s_nop 1
	v_addc_co_u32_e32 v63, vcc, 0, v17, vcc
	v_add_co_u32_e32 v64, vcc, s51, v16
	s_nop 1
	v_addc_co_u32_e32 v65, vcc, 0, v17, vcc
	v_add_co_u32_e32 v78, vcc, s52, v16
	s_nop 1
	v_addc_co_u32_e32 v79, vcc, 0, v17, vcc
	v_add_co_u32_e32 v80, vcc, s53, v16
	s_nop 1
	v_addc_co_u32_e32 v81, vcc, 0, v17, vcc
	v_add_co_u32_e32 v82, vcc, s54, v16
	s_nop 1
	v_addc_co_u32_e32 v83, vcc, 0, v17, vcc
	global_load_dword v68, v[18:19], off nt
	global_load_dword v69, v[20:21], off nt
	s_nop 0
	global_load_dword v22, v[22:23], off nt
	s_nop 0
	global_load_dword v23, v[62:63], off nt
	global_load_dword v66, v[64:65], off nt
	global_load_dword v67, v[78:79], off nt
	global_load_dword v20, v[80:81], off nt
	global_load_dword v21, v[82:83], off nt
	v_add_co_u32_e32 v18, vcc, s55, v16
	s_nop 1
	v_addc_co_u32_e32 v19, vcc, 0, v17, vcc
	v_add_co_u32_e32 v62, vcc, s57, v16
	s_nop 1
	v_addc_co_u32_e32 v63, vcc, 0, v17, vcc
	v_add_co_u32_e32 v78, vcc, s58, v16
	s_nop 1
	v_addc_co_u32_e32 v79, vcc, 0, v17, vcc
	v_add_co_u32_e32 v80, vcc, s59, v16
	s_nop 1
	v_addc_co_u32_e32 v81, vcc, 0, v17, vcc
	v_add_co_u32_e32 v82, vcc, s60, v16
	s_nop 1
	v_addc_co_u32_e32 v83, vcc, 0, v17, vcc
	v_add_co_u32_e32 v84, vcc, 0x3a000, v16
	s_nop 1
	v_addc_co_u32_e32 v85, vcc, 0, v17, vcc
	v_add_co_u32_e32 v86, vcc, 0x3c000, v16
	s_nop 1
	v_addc_co_u32_e32 v87, vcc, 0, v17, vcc
	v_add_co_u32_e32 v88, vcc, 0x3e000, v16
	s_nop 1
	v_addc_co_u32_e32 v89, vcc, 0, v17, vcc
	global_load_dword v64, v[18:19], off nt
	global_load_dword v65, v[62:63], off nt
	s_nop 0
	global_load_dword v18, v[78:79], off nt
	global_load_dword v19, v[80:81], off nt
	global_load_dword v61, v[82:83], off nt
	global_load_dword v62, v[84:85], off nt
	global_load_dword v16, v[86:87], off nt
	global_load_dword v17, v[88:89], off nt
	v_add_lshl_u32 v63, s14, v0, 2
	s_cbranch_scc1 .LBB0_164
	v_lshlrev_b32_e32 v32, 2, v32
	global_load_dword v78, v32, s[8:9] nt
	global_load_dword v79, v63, s[8:9] offset:8 nt
	s_nop 0
	global_load_dword v32, v63, s[8:9] offset:16 nt
	global_load_dword v33, v63, s[8:9] offset:24 nt
	v_add_u32_e32 v80, v34, v41
	s_waitcnt vmcnt(3)
	v_mul_f32_e32 v78, v77, v78
	s_waitcnt vmcnt(2)
	v_mul_f32_e32 v79, v76, v79
	ds_write_b32 v35, v78
	ds_write_b32 v80, v79
	s_waitcnt vmcnt(0)
	v_pk_mul_f32 v[32:33], v[30:31], v[32:33]
	s_cbranch_execnz .LBB0_31

.LBB0_31:
	s_waitcnt vmcnt(28)
	v_cndmask_b32_e64 v31, 0, 1, s[10:11]
	v_add_u32_e32 v30, v34, v42
	v_cmp_ne_u32_e64 s[4:5], 1, v31
	s_andn2_b64 vcc, exec, s[10:11]
	ds_write2_b32 v30, v32, v33 offset1:66
	s_cbranch_vccnz .LBB0_165
	global_load_dword v32, v63, s[8:9] offset:32 nt
	global_load_dword v33, v63, s[8:9] offset:40 nt
	global_load_dword v30, v63, s[8:9] offset:48 nt
	global_load_dword v31, v63, s[8:9] offset:56 nt
	v_add_u32_e32 v76, v34, v43
	s_waitcnt vmcnt(3)
	v_mul_f32_e32 v32, v74, v32
	s_waitcnt vmcnt(2)
	v_mul_f32_e32 v33, v75, v33
	ds_write2_b32 v76, v32, v33 offset1:66
	s_waitcnt vmcnt(0)
	v_pk_mul_f32 v[30:31], v[28:29], v[30:31]
	s_cbranch_execnz .LBB0_34

.LBB0_34:
	s_waitcnt vmcnt(25)
	v_add_u32_e32 v28, v34, v44
	s_and_b64 vcc, exec, s[4:5]
	ds_write2_b32 v28, v30, v31 offset1:66
	s_cbranch_vccnz .LBB0_166
	global_load_dword v30, v63, s[8:9] offset:64 nt
	global_load_dword v31, v63, s[8:9] offset:72 nt
	global_load_dword v28, v63, s[8:9] offset:80 nt
	global_load_dword v29, v63, s[8:9] offset:88 nt
	v_add_u32_e32 v32, v34, v45
	s_waitcnt vmcnt(3)
	v_mul_f32_e32 v30, v72, v30
	s_waitcnt vmcnt(2)
	v_mul_f32_e32 v31, v73, v31
	ds_write2_b32 v32, v30, v31 offset1:66
	s_waitcnt vmcnt(0)
	v_pk_mul_f32 v[28:29], v[26:27], v[28:29]
	s_cbranch_execnz .LBB0_37

.LBB0_37:
	s_waitcnt vmcnt(21)
	v_add_u32_e32 v26, v34, v46
	s_and_b64 vcc, exec, s[4:5]
	ds_write2_b32 v26, v28, v29 offset1:66
	s_cbranch_vccnz .LBB0_167
	global_load_dword v28, v63, s[8:9] offset:96 nt
	global_load_dword v29, v63, s[8:9] offset:104 nt
	global_load_dword v26, v63, s[8:9] offset:112 nt
	global_load_dword v27, v63, s[8:9] offset:120 nt
	v_add_u32_e32 v30, v34, v47
	s_waitcnt vmcnt(3)
	v_mul_f32_e32 v28, v70, v28
	s_waitcnt vmcnt(2)
	v_mul_f32_e32 v29, v71, v29
	ds_write2_b32 v30, v28, v29 offset1:66
	s_waitcnt vmcnt(0)
	v_pk_mul_f32 v[26:27], v[24:25], v[26:27]
	s_cbranch_execnz .LBB0_40

.LBB0_40:
	s_waitcnt vmcnt(17)
	v_add_u32_e32 v24, v34, v48
	s_and_b64 vcc, exec, s[4:5]
	ds_write2_b32 v24, v26, v27 offset1:66
	s_cbranch_vccnz .LBB0_168
	global_load_dword v26, v63, s[8:9] offset:128 nt
	global_load_dword v27, v63, s[8:9] offset:136 nt
	global_load_dword v24, v63, s[8:9] offset:144 nt
	global_load_dword v25, v63, s[8:9] offset:152 nt
	v_add_u32_e32 v28, v34, v49
	s_waitcnt vmcnt(3)
	v_mul_f32_e32 v26, v68, v26
	s_waitcnt vmcnt(2)
	v_mul_f32_e32 v27, v69, v27
	ds_write2_b32 v28, v26, v27 offset1:66
	s_waitcnt vmcnt(0)
	v_pk_mul_f32 v[24:25], v[22:23], v[24:25]
	s_cbranch_execnz .LBB0_43

.LBB0_43:
	s_waitcnt vmcnt(13)
	v_add_u32_e32 v22, v34, v50
	s_and_b64 vcc, exec, s[4:5]
	ds_write2_b32 v22, v24, v25 offset1:66
	s_cbranch_vccnz .LBB0_169
	global_load_dword v24, v63, s[8:9] offset:160 nt
	global_load_dword v25, v63, s[8:9] offset:168 nt
	global_load_dword v22, v63, s[8:9] offset:176 nt
	global_load_dword v23, v63, s[8:9] offset:184 nt
	v_add_u32_e32 v26, v34, v51
	s_waitcnt vmcnt(3)
	v_mul_f32_e32 v24, v66, v24
	s_waitcnt vmcnt(2)
	v_mul_f32_e32 v25, v67, v25
	ds_write2_b32 v26, v24, v25 offset1:66
	s_waitcnt vmcnt(0)
	v_pk_mul_f32 v[22:23], v[20:21], v[22:23]
	s_cbranch_execnz .LBB0_46

.LBB0_46:
	s_waitcnt vmcnt(9)
	v_add_u32_e32 v20, v34, v52
	s_and_b64 vcc, exec, s[4:5]
	ds_write2_b32 v20, v22, v23 offset1:66
	s_cbranch_vccnz .LBB0_170
	global_load_dword v22, v63, s[8:9] offset:192 nt
	global_load_dword v23, v63, s[8:9] offset:200 nt
	global_load_dword v20, v63, s[8:9] offset:208 nt
	global_load_dword v21, v63, s[8:9] offset:216 nt
	v_add_u32_e32 v24, v34, v53
	s_waitcnt vmcnt(3)
	v_mul_f32_e32 v22, v64, v22
	s_waitcnt vmcnt(2)
	v_mul_f32_e32 v23, v65, v23
	ds_write2_b32 v24, v22, v23 offset1:66
	s_waitcnt vmcnt(0)
	v_pk_mul_f32 v[20:21], v[18:19], v[20:21]
	s_cbranch_execnz .LBB0_49

.LBB0_49:
	s_waitcnt vmcnt(5)
	v_add_u32_e32 v18, v34, v53
	ds_write2_b32 v18, v20, v21 offset0:132 offset1:198
	s_and_b64 vcc, exec, s[4:5]
	v_add_u32_e32 v20, 0x400, v18
	s_cbranch_vccnz .LBB0_171
	global_load_dword v21, v63, s[8:9] offset:224 nt
	global_load_dword v22, v63, s[8:9] offset:232 nt
	global_load_dword v18, v63, s[8:9] offset:240 nt
	global_load_dword v19, v63, s[8:9] offset:248 nt
	s_waitcnt vmcnt(3)
	v_mul_f32_e32 v21, v61, v21
	s_waitcnt vmcnt(2)
	v_mul_f32_e32 v22, v62, v22
	ds_write2_b32 v20, v21, v22 offset0:8 offset1:74
	s_waitcnt vmcnt(0)
	v_pk_mul_f32 v[18:19], v[16:17], v[18:19]
	s_cbranch_execnz .LBB0_52

.LBB0_54:
	s_andn2_b64 vcc, exec, s[4:5]
	s_cbranch_vccnz .LBB0_56
	s_load_dwordx2 s[8:9], s[0:1], 0x80
	s_add_i32 s4, s21, 0x1df00
	s_and_b32 s5, s4, 0x1ffc0
	s_and_b32 s4, s7, 0x3e0
	s_lshl_b32 s10, s4, 2
	s_waitcnt lgkmcnt(0)
	s_add_u32 s8, s8, s10
	v_or_b32_e32 v18, s5, v0
	s_addc_u32 s9, s9, 0
	v_lshl_add_u64 v[16:17], s[8:9], 0, v[2:3]
	v_lshlrev_b32_e32 v18, 12, v18
	v_mov_b32_e32 v19, v3
	v_lshl_add_u64 v[16:17], v[16:17], 0, v[18:19]
	v_add_co_u32_e32 v18, vcc, s23, v16
	s_lshl_b32 s14, s5, 1
	s_nop 0
	v_addc_co_u32_e32 v19, vcc, 0, v17, vcc
	v_add_co_u32_e32 v20, vcc, s24, v16
	s_nop 1
	v_addc_co_u32_e32 v21, vcc, 0, v17, vcc
	v_add_co_u32_e32 v22, vcc, s25, v16
	s_nop 1
	v_addc_co_u32_e32 v23, vcc, 0, v17, vcc
	v_add_co_u32_e32 v24, vcc, s31, v16
	s_nop 1
	v_addc_co_u32_e32 v25, vcc, 0, v17, vcc
	v_add_co_u32_e32 v26, vcc, s36, v16
	s_nop 1
	v_addc_co_u32_e32 v27, vcc, 0, v17, vcc
	v_add_co_u32_e32 v28, vcc, s37, v16
	s_nop 1
	v_addc_co_u32_e32 v29, vcc, 0, v17, vcc
	v_add_co_u32_e32 v30, vcc, s38, v16
	s_nop 1
	v_addc_co_u32_e32 v31, vcc, 0, v17, vcc
	global_load_dword v61, v[16:17], off nt
	global_load_dword v62, v[18:19], off nt
	global_load_dword v63, v[20:21], off nt
	global_load_dword v64, v[22:23], off nt
	global_load_dword v65, v[24:25], off nt
	global_load_dword v66, v[26:27], off nt
	global_load_dword v67, v[28:29], off nt
	global_load_dword v68, v[30:31], off nt
	v_add_co_u32_e32 v18, vcc, s39, v16
	s_nop 1
	v_addc_co_u32_e32 v19, vcc, 0, v17, vcc
	v_add_co_u32_e32 v20, vcc, s40, v16
	s_nop 1
	v_addc_co_u32_e32 v21, vcc, 0, v17, vcc
	v_add_co_u32_e32 v22, vcc, s41, v16
	s_nop 1
	v_addc_co_u32_e32 v23, vcc, 0, v17, vcc
	v_add_co_u32_e32 v24, vcc, s42, v16
	s_nop 1
	v_addc_co_u32_e32 v25, vcc, 0, v17, vcc
	v_add_co_u32_e32 v26, vcc, s43, v16
	s_nop 1
	v_addc_co_u32_e32 v27, vcc, 0, v17, vcc
	v_add_co_u32_e32 v28, vcc, s44, v16
	s_nop 1
	v_addc_co_u32_e32 v29, vcc, 0, v17, vcc
	v_add_co_u32_e32 v30, vcc, s45, v16
	s_nop 1
	v_addc_co_u32_e32 v31, vcc, 0, v17, vcc
	v_add_co_u32_e32 v32, vcc, s46, v16
	s_nop 1
	v_addc_co_u32_e32 v33, vcc, 0, v17, vcc
	global_load_dword v69, v[18:19], off nt
	global_load_dword v70, v[20:21], off nt
	global_load_dword v71, v[22:23], off nt
	global_load_dword v72, v[24:25], off nt
	global_load_dword v73, v[26:27], off nt
	global_load_dword v74, v[28:29], off nt
	global_load_dword v75, v[30:31], off nt
	global_load_dword v76, v[32:33], off nt
	v_add_co_u32_e32 v18, vcc, s47, v16
	s_nop 1
	v_addc_co_u32_e32 v19, vcc, 0, v17, vcc
	v_add_co_u32_e32 v20, vcc, s48, v16
	s_nop 1
	v_addc_co_u32_e32 v21, vcc, 0, v17, vcc
	v_add_co_u32_e32 v22, vcc, s49, v16
	s_nop 1
	v_addc_co_u32_e32 v23, vcc, 0, v17, vcc
	v_add_co_u32_e32 v24, vcc, s50, v16
	s_nop 1
	v_addc_co_u32_e32 v25, vcc, 0, v17, vcc
	v_add_co_u32_e32 v26, vcc, s51, v16
	s_nop 1
	v_addc_co_u32_e32 v27, vcc, 0, v17, vcc
	v_add_co_u32_e32 v28, vcc, s52, v16
	s_nop 1
	v_addc_co_u32_e32 v29, vcc, 0, v17, vcc
	v_add_co_u32_e32 v30, vcc, s53, v16
	s_nop 1
	v_addc_co_u32_e32 v31, vcc, 0, v17, vcc
	v_add_co_u32_e32 v32, vcc, s54, v16
	s_nop 1
	v_addc_co_u32_e32 v33, vcc, 0, v17, vcc
	global_load_dword v77, v[18:19], off nt
	global_load_dword v78, v[20:21], off nt
	global_load_dword v79, v[22:23], off nt
	global_load_dword v80, v[24:25], off nt
	global_load_dword v81, v[26:27], off nt
	global_load_dword v82, v[28:29], off nt
	global_load_dword v83, v[30:31], off nt
	s_nop 0
	global_load_dword v32, v[32:33], off nt
	v_add_co_u32_e32 v18, vcc, s55, v16
	s_nop 1
	v_addc_co_u32_e32 v19, vcc, 0, v17, vcc
	v_add_co_u32_e32 v20, vcc, s57, v16
	s_nop 1
	v_addc_co_u32_e32 v21, vcc, 0, v17, vcc
	v_add_co_u32_e32 v22, vcc, s58, v16
	s_nop 1
	v_addc_co_u32_e32 v23, vcc, 0, v17, vcc
	v_add_co_u32_e32 v24, vcc, s59, v16
	s_nop 1
	v_addc_co_u32_e32 v25, vcc, 0, v17, vcc
	v_add_co_u32_e32 v26, vcc, s60, v16
	s_nop 1
	v_addc_co_u32_e32 v27, vcc, 0, v17, vcc
	v_add_co_u32_e32 v28, vcc, s61, v16
	s_nop 1
	v_addc_co_u32_e32 v29, vcc, 0, v17, vcc
	v_add_co_u32_e32 v30, vcc, s62, v16
	s_nop 1
	v_addc_co_u32_e32 v31, vcc, 0, v17, vcc
	v_add_co_u32_e32 v16, vcc, s63, v16
	s_nop 1
	v_addc_co_u32_e32 v17, vcc, 0, v17, vcc
	global_load_dword v18, v[18:19], off nt
	s_nop 0
	global_load_dword v19, v[20:21], off nt
	s_nop 0
	global_load_dword v20, v[22:23], off nt
	global_load_dword v21, v[24:25], off nt
	s_nop 0
	global_load_dword v22, v[26:27], off nt
	global_load_dword v23, v[28:29], off nt
	global_load_dword v24, v[30:31], off nt
	s_nop 0
	global_load_dword v16, v[16:17], off nt
	s_waitcnt vmcnt(30)
	ds_write2_b32 v35, v61, v62 offset1:66
	s_waitcnt vmcnt(28)
	ds_write2_b32 v35, v63, v64 offset0:132 offset1:198
	s_waitcnt vmcnt(26)
	ds_write2_b32 v54, v65, v66 offset0:8 offset1:74
	s_waitcnt vmcnt(24)
	ds_write2_b32 v54, v67, v68 offset0:140 offset1:206
	s_waitcnt vmcnt(22)
	ds_write2_b32 v55, v69, v70 offset0:16 offset1:82
	s_waitcnt vmcnt(20)
	ds_write2_b32 v55, v71, v72 offset0:148 offset1:214
	s_waitcnt vmcnt(18)
	ds_write2_b32 v56, v73, v74 offset0:24 offset1:90
	s_waitcnt vmcnt(16)
	ds_write2_b32 v56, v75, v76 offset0:156 offset1:222
	s_waitcnt vmcnt(14)
	ds_write2_b32 v57, v77, v78 offset0:32 offset1:98
	s_waitcnt vmcnt(12)
	ds_write2_b32 v57, v79, v80 offset0:164 offset1:230
	s_waitcnt vmcnt(10)
	ds_write2_b32 v58, v81, v82 offset0:40 offset1:106
	s_waitcnt vmcnt(8)
	ds_write2_b32 v58, v83, v32 offset0:172 offset1:238
	s_waitcnt vmcnt(6)
	ds_write2_b32 v59, v18, v19 offset0:48 offset1:114
	s_waitcnt vmcnt(4)
	ds_write2_b32 v59, v20, v21 offset0:180 offset1:246
	s_waitcnt vmcnt(2)
	ds_write2_b32 v60, v22, v23 offset0:56 offset1:122
	s_waitcnt vmcnt(0)
	ds_write2_b32 v60, v24, v16 offset0:188 offset1:254
	s_waitcnt lgkmcnt(0)
	ds_read2_b32 v[20:21], v37 offset1:8
	ds_read2_b32 v[24:25], v37 offset0:33 offset1:41
	ds_read2_b32 v[26:27], v37 offset0:66 offset1:74
	ds_read2_b32 v[28:29], v37 offset0:99 offset1:107
	ds_read2_b32 v[30:31], v37 offset0:132 offset1:140
	s_waitcnt lgkmcnt(4)
	v_bfe_u32 v16, v20, 16, 1
	v_add3_u32 v16, v20, v16, s64
	s_waitcnt lgkmcnt(3)
	v_bfe_u32 v17, v24, 16, 1
	v_lshrrev_b32_e32 v16, 16, v16
	v_add3_u32 v17, v24, v17, s64
	ds_read2_b32 v[32:33], v37 offset0:165 offset1:173
	v_and_or_b32 v16, v17, s65, v16
	s_waitcnt lgkmcnt(3)
	v_bfe_u32 v17, v26, 16, 1
	v_add3_u32 v17, v26, v17, s64
	s_waitcnt lgkmcnt(2)
	v_bfe_u32 v18, v28, 16, 1
	ds_read2_b32 v[62:63], v37 offset0:198 offset1:206
	v_lshrrev_b32_e32 v17, 16, v17
	v_add3_u32 v18, v28, v18, s64
	ds_read2_b32 v[64:65], v37 offset0:231 offset1:239
	v_and_or_b32 v17, v18, s65, v17
	s_waitcnt lgkmcnt(3)
	v_bfe_u32 v18, v30, 16, 1
	v_add3_u32 v18, v30, v18, s64
	s_waitcnt lgkmcnt(2)
	v_bfe_u32 v19, v32, 16, 1
	v_lshrrev_b32_e32 v18, 16, v18
	v_add3_u32 v19, v32, v19, s64
	v_and_or_b32 v18, v19, s65, v18
	s_waitcnt lgkmcnt(1)
	v_bfe_u32 v19, v62, 16, 1
	v_add3_u32 v19, v62, v19, s64
	s_waitcnt lgkmcnt(0)
	v_bfe_u32 v20, v64, 16, 1
	v_lshrrev_b32_e32 v19, 16, v19
	v_add3_u32 v20, v64, v20, s64
	v_and_or_b32 v19, v20, s65, v19
	v_or_b32_e32 v20, s4, v36
	v_mul_u32_u24_e32 v20, 0xb00, v20
	v_lshl_add_u64 v[22:23], v[10:11], 0, s[14:15]
	v_lshlrev_b32_e32 v66, 1, v20
	v_mov_b32_e32 v67, v3
	v_lshl_add_u64 v[66:67], v[22:23], 0, v[66:67]
	global_store_dwordx4 v[66:67], v[16:19], off
	v_bfe_u32 v20, v65, 16, 1
	v_add3_u32 v20, v65, v20, s64
	v_bfe_u32 v16, v21, 16, 1
	v_add3_u32 v16, v21, v16, s64
	v_bfe_u32 v17, v25, 16, 1
	v_lshrrev_b32_e32 v16, 16, v16
	v_add3_u32 v17, v25, v17, s64
	v_and_or_b32 v16, v17, s65, v16
	v_bfe_u32 v17, v27, 16, 1
	v_add3_u32 v17, v27, v17, s64
	v_bfe_u32 v18, v29, 16, 1
	v_lshrrev_b32_e32 v17, 16, v17
	v_add3_u32 v18, v29, v18, s64
	v_and_or_b32 v17, v18, s65, v17
	v_bfe_u32 v18, v31, 16, 1
	v_add3_u32 v18, v31, v18, s64
	v_bfe_u32 v19, v33, 16, 1
	v_lshrrev_b32_e32 v18, 16, v18
	v_add3_u32 v19, v33, v19, s64
	v_and_or_b32 v18, v19, s65, v18
	v_bfe_u32 v19, v63, 16, 1
	v_add3_u32 v19, v63, v19, s64
	v_lshrrev_b32_e32 v19, 16, v19
	v_and_or_b32 v19, v20, s65, v19
	v_or_b32_e32 v20, s4, v38
	v_mul_u32_u24_e32 v20, 0xb00, v20
	v_lshlrev_b32_e32 v20, 1, v20
	v_mov_b32_e32 v21, v3
	ds_read2_b32 v[24:25], v37 offset0:16 offset1:24
	v_lshl_add_u64 v[20:21], v[22:23], 0, v[20:21]
	global_store_dwordx4 v[20:21], v[16:19], off
	ds_read2_b32 v[20:21], v37 offset0:49 offset1:57
	ds_read2_b32 v[26:27], v37 offset0:82 offset1:90
	ds_read2_b32 v[28:29], v37 offset0:115 offset1:123
	s_waitcnt lgkmcnt(3)
	v_bfe_u32 v16, v24, 16, 1
	v_add3_u32 v16, v24, v16, s64
	s_waitcnt lgkmcnt(2)
	v_bfe_u32 v17, v20, 16, 1
	ds_read2_b32 v[30:31], v37 offset0:148 offset1:156
	v_lshrrev_b32_e32 v16, 16, v16
	v_add3_u32 v17, v20, v17, s64
	ds_read2_b32 v[32:33], v37 offset0:181 offset1:189
	v_and_or_b32 v16, v17, s65, v16
	s_waitcnt lgkmcnt(3)
	v_bfe_u32 v17, v26, 16, 1
	v_add3_u32 v17, v26, v17, s64
	s_waitcnt lgkmcnt(2)
	v_bfe_u32 v18, v28, 16, 1
	ds_read2_b32 v[62:63], v37 offset0:214 offset1:222
	v_lshrrev_b32_e32 v17, 16, v17
	v_add3_u32 v18, v28, v18, s64
	ds_read2_b32 v[64:65], v37 offset0:247 offset1:255
	v_and_or_b32 v17, v18, s65, v17
	s_waitcnt lgkmcnt(3)
	v_bfe_u32 v18, v30, 16, 1
	v_add3_u32 v18, v30, v18, s64
	s_waitcnt lgkmcnt(2)
	v_bfe_u32 v19, v32, 16, 1
	v_lshrrev_b32_e32 v18, 16, v18
	v_add3_u32 v19, v32, v19, s64
	v_and_or_b32 v18, v19, s65, v18
	s_waitcnt lgkmcnt(1)
	v_bfe_u32 v19, v62, 16, 1
	v_add3_u32 v19, v62, v19, s64
	s_waitcnt lgkmcnt(0)
	v_bfe_u32 v20, v64, 16, 1
	v_lshrrev_b32_e32 v19, 16, v19
	v_add3_u32 v20, v64, v20, s64
	v_and_or_b32 v19, v20, s65, v19
	v_or_b32_e32 v20, s4, v39
	v_mul_u32_u24_e32 v20, 0xb00, v20
	v_lshlrev_b32_e32 v66, 1, v20
	v_mov_b32_e32 v67, v3
	v_lshl_add_u64 v[66:67], v[22:23], 0, v[66:67]
	global_store_dwordx4 v[66:67], v[16:19], off
	v_or_b32_e32 v20, s4, v40
	v_mul_u32_u24_e32 v20, 0xb00, v20
	v_bfe_u32 v17, v25, 16, 1
	v_bfe_u32 v16, v21, 16, 1
	v_add3_u32 v17, v25, v17, s64
	v_add3_u32 v16, v21, v16, s64
	v_lshrrev_b32_e32 v17, 16, v17
	v_bfe_u32 v18, v27, 16, 1
	v_and_or_b32 v16, v16, s65, v17
	v_bfe_u32 v17, v29, 16, 1
	v_add3_u32 v18, v27, v18, s64
	v_add3_u32 v17, v29, v17, s64
	v_lshrrev_b32_e32 v18, 16, v18
	v_bfe_u32 v19, v31, 16, 1
	v_and_or_b32 v17, v17, s65, v18
	v_bfe_u32 v18, v33, 16, 1
	v_add3_u32 v19, v31, v19, s64
	v_add3_u32 v18, v33, v18, s64
	v_lshrrev_b32_e32 v19, 16, v19
	v_bfe_u32 v21, v63, 16, 1
	v_and_or_b32 v18, v18, s65, v19
	v_bfe_u32 v19, v65, 16, 1
	v_add3_u32 v21, v63, v21, s64
	v_add3_u32 v19, v65, v19, s64
	v_lshrrev_b32_e32 v21, 16, v21
	v_and_or_b32 v19, v19, s65, v21
	v_lshlrev_b32_e32 v20, 1, v20
	v_mov_b32_e32 v21, v3
	v_lshl_add_u64 v[20:21], v[22:23], 0, v[20:21]
	global_store_dwordx4 v[20:21], v[16:19], off
	s_waitcnt lgkmcnt(0)

.LBB0_57:
	s_andn2_b64 vcc, exec, s[4:5]
	s_cbranch_vccnz .LBB0_83
	s_add_i32 s4, s94, 0xfa80
	s_and_b32 s5, s4, 0xffff
	s_mul_i32 s5, s5, 0xba2f
	s_load_dwordx4 s[8:11], s[0:1], 0x60
	s_lshr_b32 s5, s5, 23
	s_mul_i32 s14, s5, 0xb0
	s_sub_i32 s16, s4, s14
	s_lshl_b32 s4, s16, 7
	s_lshl_b32 s14, s5, 6
	s_and_b32 s4, s4, 0x3ff80
	v_or_b32_e32 v32, s14, v0
	s_waitcnt lgkmcnt(0)
	s_add_u32 s4, s10, s4
	s_addc_u32 s5, s11, 0
	v_mul_u32_u24_e32 v20, 0x1600, v32
	v_lshl_add_u64 v[16:17], s[4:5], 0, v[2:3]
	v_lshlrev_b32_e32 v20, 2, v20
	v_mov_b32_e32 v21, v3
	v_mad_u64_u32 v[18:19], s[4:5], v32, s66, v[16:17]
	v_lshl_add_u64 v[16:17], v[16:17], 0, v[20:21]
	v_add_co_u32_e32 v20, vcc, s67, v16
	s_cmp_lg_u64 s[8:9], 0
	s_nop 0
	v_addc_co_u32_e32 v21, vcc, 0, v17, vcc
	v_add_co_u32_e32 v22, vcc, s42, v16
	s_cselect_b64 s[10:11], -1, 0
	s_nop 0
	v_addc_co_u32_e32 v23, vcc, 0, v17, vcc
	v_add_co_u32_e32 v24, vcc, s68, v16
	s_cmp_eq_u64 s[8:9], 0
	s_nop 0
	v_addc_co_u32_e32 v25, vcc, 0, v17, vcc
	v_add_co_u32_e32 v26, vcc, s53, v16
	s_nop 1
	v_addc_co_u32_e32 v27, vcc, 0, v17, vcc
	v_add_co_u32_e32 v28, vcc, s69, v16
	s_nop 1
	v_addc_co_u32_e32 v29, vcc, 0, v17, vcc
	v_add_co_u32_e32 v62, vcc, s70, v16
	s_nop 1
	v_addc_co_u32_e32 v63, vcc, 0, v17, vcc
	v_add_co_u32_e32 v64, vcc, s71, v16
	s_nop 1
	v_addc_co_u32_e32 v65, vcc, 0, v17, vcc
	global_load_dword v77, v[18:19], off nt
	global_load_dword v76, v[20:21], off nt
	global_load_dword v30, v[22:23], off nt
	global_load_dword v31, v[24:25], off nt
	global_load_dword v74, v[26:27], off nt
	global_load_dword v75, v[28:29], off nt
	s_nop 0
	global_load_dword v28, v[62:63], off nt
	global_load_dword v29, v[64:65], off nt
	v_add_co_u32_e32 v18, vcc, s72, v16
	s_nop 1
	v_addc_co_u32_e32 v19, vcc, 0, v17, vcc
	v_add_co_u32_e32 v20, vcc, s73, v16
	s_nop 1
	v_addc_co_u32_e32 v21, vcc, 0, v17, vcc
	v_add_co_u32_e32 v22, vcc, s74, v16
	s_nop 1
	v_addc_co_u32_e32 v23, vcc, 0, v17, vcc
	v_add_co_u32_e32 v24, vcc, s75, v16
	s_nop 1
	v_addc_co_u32_e32 v25, vcc, 0, v17, vcc
	v_add_co_u32_e32 v62, vcc, s76, v16
	s_nop 1
	v_addc_co_u32_e32 v63, vcc, 0, v17, vcc
	v_add_co_u32_e32 v64, vcc, s77, v16
	s_nop 1
	v_addc_co_u32_e32 v65, vcc, 0, v17, vcc
	v_add_co_u32_e32 v66, vcc, s78, v16
	s_nop 1
	v_addc_co_u32_e32 v67, vcc, 0, v17, vcc
	v_add_co_u32_e32 v68, vcc, s79, v16
	s_nop 1
	v_addc_co_u32_e32 v69, vcc, 0, v17, vcc
	global_load_dword v72, v[18:19], off nt
	global_load_dword v73, v[20:21], off nt
	global_load_dword v26, v[22:23], off nt
	global_load_dword v27, v[24:25], off nt
	global_load_dword v70, v[62:63], off nt
	global_load_dword v71, v[64:65], off nt
	s_nop 0
	global_load_dword v24, v[66:67], off nt
	global_load_dword v25, v[68:69], off nt
	v_add_co_u32_e32 v18, vcc, s80, v16
	s_nop 1
	v_addc_co_u32_e32 v19, vcc, 0, v17, vcc
	v_add_co_u32_e32 v20, vcc, s81, v16
	s_nop 1
	v_addc_co_u32_e32 v21, vcc, 0, v17, vcc
	v_add_co_u32_e32 v22, vcc, s82, v16
	s_nop 1
	v_addc_co_u32_e32 v23, vcc, 0, v17, vcc
	v_add_co_u32_e32 v62, vcc, s83, v16
	s_nop 1
	v_addc_co_u32_e32 v63, vcc, 0, v17, vcc
	v_add_co_u32_e32 v64, vcc, s84, v16
	s_nop 1
	v_addc_co_u32_e32 v65, vcc, 0, v17, vcc
	v_add_co_u32_e32 v78, vcc, s85, v16
	s_nop 1
	v_addc_co_u32_e32 v79, vcc, 0, v17, vcc
	v_add_co_u32_e32 v80, vcc, s86, v16
	s_nop 1
	v_addc_co_u32_e32 v81, vcc, 0, v17, vcc
	v_add_co_u32_e32 v82, vcc, s87, v16
	s_nop 1
	v_addc_co_u32_e32 v83, vcc, 0, v17, vcc
	global_load_dword v68, v[18:19], off nt
	global_load_dword v69, v[20:21], off nt
	s_nop 0
	global_load_dword v22, v[22:23], off nt
	s_nop 0
	global_load_dword v23, v[62:63], off nt
	global_load_dword v66, v[64:65], off nt
	global_load_dword v67, v[78:79], off nt
	global_load_dword v20, v[80:81], off nt
	global_load_dword v21, v[82:83], off nt
	v_add_co_u32_e32 v18, vcc, s88, v16
	s_nop 1
	v_addc_co_u32_e32 v19, vcc, 0, v17, vcc
	v_add_co_u32_e32 v62, vcc, s89, v16
	s_nop 1
	v_addc_co_u32_e32 v63, vcc, 0, v17, vcc
	v_add_co_u32_e32 v78, vcc, s90, v16
	s_nop 1
	v_addc_co_u32_e32 v79, vcc, 0, v17, vcc
	v_add_co_u32_e32 v80, vcc, s91, v16
	s_nop 1
	v_addc_co_u32_e32 v81, vcc, 0, v17, vcc
	v_add_co_u32_e32 v82, vcc, s92, v16
	s_nop 1
	v_addc_co_u32_e32 v83, vcc, 0, v17, vcc
	v_add_co_u32_e32 v84, vcc, 0x13f000, v16
	s_nop 1
	v_addc_co_u32_e32 v85, vcc, 0, v17, vcc
	v_add_co_u32_e32 v86, vcc, 0x14a000, v16
	s_nop 1
	v_addc_co_u32_e32 v87, vcc, 0, v17, vcc
	v_add_co_u32_e32 v88, vcc, 0x155000, v16
	s_nop 1
	v_addc_co_u32_e32 v89, vcc, 0, v17, vcc
	global_load_dword v64, v[18:19], off nt
	global_load_dword v65, v[62:63], off nt
	s_nop 0
	global_load_dword v18, v[78:79], off nt
	global_load_dword v19, v[80:81], off nt
	global_load_dword v61, v[82:83], off nt
	global_load_dword v62, v[84:85], off nt
	global_load_dword v16, v[86:87], off nt
	global_load_dword v17, v[88:89], off nt
	v_add_lshl_u32 v63, v0, s14, 2
	s_cbranch_scc1 .LBB0_156
	v_lshlrev_b32_e32 v32, 2, v32
	global_load_dword v78, v32, s[8:9] nt
	global_load_dword v79, v63, s[8:9] offset:8 nt
	s_nop 0
	global_load_dword v32, v63, s[8:9] offset:16 nt
	global_load_dword v33, v63, s[8:9] offset:24 nt
	v_add_u32_e32 v80, v34, v41
	s_waitcnt vmcnt(3)
	v_mul_f32_e32 v78, v77, v78
	s_waitcnt vmcnt(2)
	v_mul_f32_e32 v79, v76, v79
	ds_write_b32 v35, v78
	ds_write_b32 v80, v79
	s_waitcnt vmcnt(0)
	v_pk_mul_f32 v[32:33], v[30:31], v[32:33]
	s_cbranch_execnz .LBB0_61

.LBB0_89:
	s_add_i32 s10, s21, 0xfffff900
	s_and_b32 s16, s7, 0x3e0
	s_and_b32 s14, s10, 0x1ffc0
	s_lshl_b32 s10, s16, 2
	s_waitcnt lgkmcnt(0)
	s_add_u32 s4, s4, s10
	v_or_b32_e32 v32, s14, v0
	s_addc_u32 s5, s5, 0
	v_lshl_add_u64 v[16:17], s[4:5], 0, v[2:3]
	v_lshlrev_b32_e32 v18, 12, v32
	v_mov_b32_e32 v19, v3
	v_lshl_add_u64 v[16:17], v[16:17], 0, v[18:19]
	v_add_co_u32_e32 v18, vcc, s23, v16
	s_cmp_lg_u64 s[8:9], 0
	s_nop 0
	v_addc_co_u32_e32 v19, vcc, 0, v17, vcc
	v_add_co_u32_e32 v20, vcc, s24, v16
	s_cselect_b64 s[10:11], -1, 0
	s_nop 0
	v_addc_co_u32_e32 v21, vcc, 0, v17, vcc
	v_add_co_u32_e32 v22, vcc, s25, v16
	s_cmp_eq_u64 s[8:9], 0
	s_nop 0
	v_addc_co_u32_e32 v23, vcc, 0, v17, vcc
	v_add_co_u32_e32 v24, vcc, s31, v16
	s_nop 1
	v_addc_co_u32_e32 v25, vcc, 0, v17, vcc
	v_add_co_u32_e32 v26, vcc, s36, v16
	s_nop 1
	v_addc_co_u32_e32 v27, vcc, 0, v17, vcc
	v_add_co_u32_e32 v28, vcc, s37, v16
	s_nop 1
	v_addc_co_u32_e32 v29, vcc, 0, v17, vcc
	v_add_co_u32_e32 v62, vcc, s38, v16
	s_nop 1
	v_addc_co_u32_e32 v63, vcc, 0, v17, vcc
	global_load_dword v77, v[16:17], off nt
	global_load_dword v76, v[18:19], off nt
	global_load_dword v30, v[20:21], off nt
	global_load_dword v31, v[22:23], off nt
	global_load_dword v74, v[24:25], off nt
	global_load_dword v75, v[26:27], off nt
	s_nop 0
	global_load_dword v28, v[28:29], off nt
	s_nop 0
	global_load_dword v29, v[62:63], off nt
	v_add_co_u32_e32 v18, vcc, s39, v16
	s_nop 1
	v_addc_co_u32_e32 v19, vcc, 0, v17, vcc
	v_add_co_u32_e32 v20, vcc, s40, v16
	s_nop 1
	v_addc_co_u32_e32 v21, vcc, 0, v17, vcc
	v_add_co_u32_e32 v22, vcc, s41, v16
	s_nop 1
	v_addc_co_u32_e32 v23, vcc, 0, v17, vcc
	v_add_co_u32_e32 v24, vcc, s42, v16
	s_nop 1
	v_addc_co_u32_e32 v25, vcc, 0, v17, vcc
	v_add_co_u32_e32 v62, vcc, s43, v16
	s_nop 1
	v_addc_co_u32_e32 v63, vcc, 0, v17, vcc
	v_add_co_u32_e32 v64, vcc, s44, v16
	s_nop 1
	v_addc_co_u32_e32 v65, vcc, 0, v17, vcc
	v_add_co_u32_e32 v66, vcc, s45, v16
	s_nop 1
	v_addc_co_u32_e32 v67, vcc, 0, v17, vcc
	v_add_co_u32_e32 v68, vcc, s46, v16
	s_nop 1
	v_addc_co_u32_e32 v69, vcc, 0, v17, vcc
	global_load_dword v72, v[18:19], off nt
	global_load_dword v73, v[20:21], off nt
	global_load_dword v26, v[22:23], off nt
	global_load_dword v27, v[24:25], off nt
	global_load_dword v70, v[62:63], off nt
	global_load_dword v71, v[64:65], off nt
	s_nop 0
	global_load_dword v24, v[66:67], off nt
	global_load_dword v25, v[68:69], off nt
	v_add_co_u32_e32 v18, vcc, s47, v16
	s_nop 1
	v_addc_co_u32_e32 v19, vcc, 0, v17, vcc
	v_add_co_u32_e32 v20, vcc, s48, v16
	s_nop 1
	v_addc_co_u32_e32 v21, vcc, 0, v17, vcc
	v_add_co_u32_e32 v22, vcc, s49, v16
	s_nop 1
	v_addc_co_u32_e32 v23, vcc, 0, v17, vcc
	v_add_co_u32_e32 v62, vcc, s50, v16
	s_nop 1
	v_addc_co_u32_e32 v63, vcc, 0, v17, vcc
	v_add_co_u32_e32 v64, vcc, s51, v16
	s_nop 1
	v_addc_co_u32_e32 v65, vcc, 0, v17, vcc
	v_add_co_u32_e32 v78, vcc, s52, v16
	s_nop 1
	v_addc_co_u32_e32 v79, vcc, 0, v17, vcc
	v_add_co_u32_e32 v80, vcc, s53, v16
	s_nop 1
	v_addc_co_u32_e32 v81, vcc, 0, v17, vcc
	v_add_co_u32_e32 v82, vcc, s54, v16
	s_nop 1
	v_addc_co_u32_e32 v83, vcc, 0, v17, vcc
	global_load_dword v68, v[18:19], off nt
	global_load_dword v69, v[20:21], off nt
	s_nop 0
	global_load_dword v22, v[22:23], off nt
	s_nop 0
	global_load_dword v23, v[62:63], off nt
	global_load_dword v66, v[64:65], off nt
	global_load_dword v67, v[78:79], off nt
	global_load_dword v20, v[80:81], off nt
	global_load_dword v21, v[82:83], off nt
	v_add_co_u32_e32 v18, vcc, s55, v16
	s_nop 1
	v_addc_co_u32_e32 v19, vcc, 0, v17, vcc
	v_add_co_u32_e32 v62, vcc, s57, v16
	s_nop 1
	v_addc_co_u32_e32 v63, vcc, 0, v17, vcc
	v_add_co_u32_e32 v78, vcc, s58, v16
	s_nop 1
	v_addc_co_u32_e32 v79, vcc, 0, v17, vcc
	v_add_co_u32_e32 v80, vcc, s59, v16
	s_nop 1
	v_addc_co_u32_e32 v81, vcc, 0, v17, vcc
	v_add_co_u32_e32 v82, vcc, s60, v16
	s_nop 1
	v_addc_co_u32_e32 v83, vcc, 0, v17, vcc
	v_add_co_u32_e32 v84, vcc, 0x3a000, v16
	s_nop 1
	v_addc_co_u32_e32 v85, vcc, 0, v17, vcc
	v_add_co_u32_e32 v86, vcc, 0x3c000, v16
	s_nop 1
	v_addc_co_u32_e32 v87, vcc, 0, v17, vcc
	v_add_co_u32_e32 v88, vcc, 0x3e000, v16
	s_nop 1
	v_addc_co_u32_e32 v89, vcc, 0, v17, vcc
	global_load_dword v64, v[18:19], off nt
	global_load_dword v65, v[62:63], off nt
	s_nop 0
	global_load_dword v18, v[78:79], off nt
	global_load_dword v19, v[80:81], off nt
	global_load_dword v61, v[82:83], off nt
	global_load_dword v62, v[84:85], off nt
	global_load_dword v16, v[86:87], off nt
	global_load_dword v17, v[88:89], off nt
	v_add_lshl_u32 v63, s14, v0, 2
	s_cbranch_scc1 .LBB0_148
	v_lshlrev_b32_e32 v32, 2, v32
	global_load_dword v78, v32, s[8:9] nt
	global_load_dword v79, v63, s[8:9] offset:8 nt
	s_nop 0
	global_load_dword v32, v63, s[8:9] offset:16 nt
	global_load_dword v33, v63, s[8:9] offset:24 nt
	v_add_u32_e32 v80, v34, v41
	s_waitcnt vmcnt(3)
	v_mul_f32_e32 v78, v77, v78
	s_waitcnt vmcnt(2)
	v_mul_f32_e32 v79, v76, v79
	ds_write_b32 v35, v78
	ds_write_b32 v80, v79
	s_waitcnt vmcnt(0)
	v_pk_mul_f32 v[32:33], v[30:31], v[32:33]
	s_cbranch_execnz .LBB0_92

.LBB0_115:
	s_andn2_b64 vcc, exec, s[4:5]
	s_cbranch_vccnz .LBB0_20
	s_mul_hi_i32 s4, s94, 0x92492493
	s_add_i32 s4, s4, s94
	s_lshr_b32 s5, s4, 31
	s_ashr_i32 s4, s4, 5
	s_load_dwordx4 s[8:11], s[0:1], 0x10
	s_add_i32 s4, s4, s5
	s_lshl_b32 s18, s4, 6
	s_mulk_i32 s4, 0xf900
	s_add_i32 s16, s7, s4
	s_ashr_i32 s17, s16, 31
	s_lshl_b64 s[4:5], s[16:17], 2
	s_waitcnt lgkmcnt(0)
	s_add_u32 s4, s10, s4
	v_or_b32_e32 v32, s18, v0
	s_addc_u32 s5, s11, s5
	v_lshl_add_u64 v[16:17], s[4:5], 0, v[2:3]
	v_or_b32_e32 v26, 8, v32
	v_or_b32_e32 v28, 10, v32
	v_or_b32_e32 v30, 12, v32
	v_mad_i64_i32 v[18:19], s[4:5], v32, s93, v[16:17]
	v_or_b32_e32 v20, 2, v32
	v_or_b32_e32 v22, 4, v32
	v_or_b32_e32 v24, 6, v32
	v_mad_i64_i32 v[26:27], s[4:5], v26, s93, v[16:17]
	v_mad_i64_i32 v[28:29], s[4:5], v28, s93, v[16:17]
	v_mad_i64_i32 v[62:63], s[4:5], v30, s93, v[16:17]
	v_or_b32_e32 v30, 14, v32
	v_mad_i64_i32 v[20:21], s[4:5], v20, s93, v[16:17]
	v_mad_i64_i32 v[22:23], s[4:5], v22, s93, v[16:17]
	v_mad_i64_i32 v[24:25], s[4:5], v24, s93, v[16:17]
	v_mad_i64_i32 v[64:65], s[4:5], v30, s93, v[16:17]
	global_load_dword v75, v[18:19], off nt
	global_load_dword v76, v[20:21], off nt
	global_load_dword v30, v[22:23], off nt
	global_load_dword v31, v[24:25], off nt
	global_load_dword v73, v[26:27], off nt
	global_load_dword v74, v[28:29], off nt
	s_nop 0
	global_load_dword v28, v[62:63], off nt
	global_load_dword v29, v[64:65], off nt
	v_or_b32_e32 v26, 24, v32
	v_mad_i64_i32 v[62:63], s[4:5], v26, s93, v[16:17]
	v_or_b32_e32 v26, 26, v32
	v_or_b32_e32 v18, 16, v32
	v_or_b32_e32 v24, 22, v32
	v_mad_i64_i32 v[64:65], s[4:5], v26, s93, v[16:17]
	v_or_b32_e32 v26, 28, v32
	v_mad_i64_i32 v[18:19], s[4:5], v18, s93, v[16:17]
	v_or_b32_e32 v20, 18, v32
	v_or_b32_e32 v22, 20, v32
	v_mad_i64_i32 v[24:25], s[4:5], v24, s93, v[16:17]
	v_mad_i64_i32 v[66:67], s[4:5], v26, s93, v[16:17]
	v_or_b32_e32 v26, 30, v32
	v_or_b32_e32 v33, 38, v32
	v_mad_i64_i32 v[20:21], s[4:5], v20, s93, v[16:17]
	v_mad_i64_i32 v[22:23], s[4:5], v22, s93, v[16:17]
	v_mad_i64_i32 v[78:79], s[4:5], v26, s93, v[16:17]
	global_load_dword v71, v[18:19], off nt
	global_load_dword v72, v[20:21], off nt
	global_load_dword v26, v[22:23], off nt
	global_load_dword v27, v[24:25], off nt
	global_load_dword v69, v[62:63], off nt
	global_load_dword v70, v[64:65], off nt
	s_nop 0
	global_load_dword v24, v[66:67], off nt
	global_load_dword v25, v[78:79], off nt
	v_mad_i64_i32 v[62:63], s[4:5], v33, s93, v[16:17]
	v_or_b32_e32 v33, 40, v32
	v_mad_i64_i32 v[64:65], s[4:5], v33, s93, v[16:17]
	v_or_b32_e32 v33, 42, v32
	v_mad_i64_i32 v[78:79], s[4:5], v33, s93, v[16:17]
	v_or_b32_e32 v33, 44, v32
	v_or_b32_e32 v18, 32, v32
	v_or_b32_e32 v20, 34, v32
	v_or_b32_e32 v22, 36, v32
	v_mad_i64_i32 v[80:81], s[4:5], v33, s93, v[16:17]
	v_or_b32_e32 v33, 46, v32
	v_mad_i64_i32 v[18:19], s[4:5], v18, s93, v[16:17]
	v_mad_i64_i32 v[20:21], s[4:5], v20, s93, v[16:17]
	v_mad_i64_i32 v[22:23], s[4:5], v22, s93, v[16:17]
	v_mad_i64_i32 v[82:83], s[4:5], v33, s93, v[16:17]
	v_or_b32_e32 v33, 50, v32
	global_load_dword v67, v[18:19], off nt
	global_load_dword v68, v[20:21], off nt
	s_nop 0
	global_load_dword v22, v[22:23], off nt
	s_nop 0
	global_load_dword v23, v[62:63], off nt
	s_nop 0
	global_load_dword v65, v[64:65], off nt
	s_nop 0
	global_load_dword v66, v[78:79], off nt
	global_load_dword v20, v[80:81], off nt
	global_load_dword v21, v[82:83], off nt
	v_mad_i64_i32 v[78:79], s[4:5], v33, s93, v[16:17]
	v_or_b32_e32 v33, 52, v32
	v_mad_i64_i32 v[80:81], s[4:5], v33, s93, v[16:17]
	v_or_b32_e32 v33, 54, v32
	v_mad_i64_i32 v[82:83], s[4:5], v33, s93, v[16:17]
	v_or_b32_e32 v33, 56, v32
	v_mad_i64_i32 v[84:85], s[4:5], v33, s93, v[16:17]
	v_or_b32_e32 v33, 58, v32
	v_or_b32_e32 v18, 48, v32
	v_mad_i64_i32 v[86:87], s[4:5], v33, s93, v[16:17]
	v_or_b32_e32 v33, 60, v32
	v_mad_i64_i32 v[18:19], s[4:5], v18, s93, v[16:17]
	v_mad_i64_i32 v[88:89], s[4:5], v33, s93, v[16:17]
	v_or_b32_e32 v33, 62, v32
	v_mad_i64_i32 v[90:91], s[4:5], v33, s93, v[16:17]
	global_load_dword v63, v[18:19], off nt
	global_load_dword v64, v[78:79], off nt
	s_nop 0
	global_load_dword v18, v[80:81], off nt
	global_load_dword v19, v[82:83], off nt
	global_load_dword v61, v[84:85], off nt
	global_load_dword v62, v[86:87], off nt
	global_load_dword v16, v[88:89], off nt
	global_load_dword v17, v[90:91], off nt
	s_cmp_lg_u64 s[8:9], 0
	s_cselect_b64 s[10:11], -1, 0
	s_cmp_eq_u64 s[8:9], 0
	v_add_u32_e32 v77, v34, v41
	s_cbranch_scc1 .LBB0_139
	v_ashrrev_i32_e32 v33, 31, v32
	s_ashr_i32 s19, s18, 31
	v_lshl_add_u64 v[32:33], v[32:33], 2, s[8:9]
	v_lshl_add_u64 v[78:79], s[18:19], 0, v[0:1]
	v_lshl_add_u64 v[78:79], v[78:79], 2, s[8:9]
	global_load_dword v80, v[32:33], off nt
	global_load_dword v81, v[78:79], off offset:8 nt
	s_nop 0
	global_load_dword v32, v[78:79], off offset:16 nt
	global_load_dword v33, v[78:79], off offset:24 nt
	s_waitcnt vmcnt(3)
	v_mul_f32_e32 v78, v75, v80
	s_waitcnt vmcnt(2)
	v_mul_f32_e32 v79, v76, v81
	ds_write_b32 v35, v78
	s_waitcnt vmcnt(0)
	v_pk_mul_f32 v[32:33], v[30:31], v[32:33]
	ds_write_b32 v77, v79
	s_cbranch_execnz .LBB0_119

.LBB0_119:
	s_waitcnt vmcnt(29)
	v_add_u32_e32 v30, v34, v42
	ds_write2_b32 v30, v32, v33 offset1:66
	v_cndmask_b32_e64 v30, 0, 1, s[10:11]
	v_cmp_ne_u32_e64 s[4:5], 1, v30
	s_andn2_b64 vcc, exec, s[10:11]
	v_add_u32_e32 v32, v34, v43
	s_cbranch_vccnz .LBB0_140
	s_ashr_i32 s19, s18, 31
	s_waitcnt vmcnt(28)
	v_lshl_add_u64 v[30:31], s[18:19], 0, v[0:1]
	v_lshl_add_u64 v[30:31], v[30:31], 2, s[8:9]
	global_load_dword v33, v[30:31], off offset:32 nt
	global_load_dword v75, v[30:31], off offset:40 nt
	global_load_dword v76, v[30:31], off offset:48 nt
	global_load_dword v77, v[30:31], off offset:56 nt
	s_waitcnt vmcnt(3)
	v_mul_f32_e32 v33, v73, v33
	s_waitcnt vmcnt(2)
	v_mul_f32_e32 v75, v74, v75
	ds_write2_b32 v32, v33, v75 offset1:66
	s_waitcnt vmcnt(0)
	v_pk_mul_f32 v[30:31], v[28:29], v[76:77]
	s_cbranch_execnz .LBB0_122

.LBB0_122:
	s_waitcnt vmcnt(25)
	v_add_u32_e32 v28, v34, v44
	ds_write2_b32 v28, v30, v31 offset1:66
	s_and_b64 vcc, exec, s[4:5]
	v_add_u32_e32 v30, v34, v45
	s_cbranch_vccnz .LBB0_141
	s_ashr_i32 s19, s18, 31
	s_waitcnt vmcnt(24)
	v_lshl_add_u64 v[28:29], s[18:19], 0, v[0:1]
	v_lshl_add_u64 v[28:29], v[28:29], 2, s[8:9]
	global_load_dword v31, v[28:29], off offset:64 nt
	global_load_dword v73, v[28:29], off offset:72 nt
	global_load_dword v32, v[28:29], off offset:80 nt
	global_load_dword v33, v[28:29], off offset:88 nt
	s_waitcnt vmcnt(3)
	v_mul_f32_e32 v31, v71, v31
	s_waitcnt vmcnt(2)
	v_mul_f32_e32 v73, v72, v73
	ds_write2_b32 v30, v31, v73 offset1:66
	s_waitcnt vmcnt(0)
	v_pk_mul_f32 v[28:29], v[26:27], v[32:33]
	s_cbranch_execnz .LBB0_125

.LBB0_125:
	s_waitcnt vmcnt(21)
	v_add_u32_e32 v26, v34, v46
	ds_write2_b32 v26, v28, v29 offset1:66
	s_and_b64 vcc, exec, s[4:5]
	v_add_u32_e32 v28, v34, v47
	s_cbranch_vccnz .LBB0_142
	s_ashr_i32 s19, s18, 31
	s_waitcnt vmcnt(20)
	v_lshl_add_u64 v[26:27], s[18:19], 0, v[0:1]
	v_lshl_add_u64 v[26:27], v[26:27], 2, s[8:9]
	global_load_dword v29, v[26:27], off offset:96 nt
	global_load_dword v32, v[26:27], off offset:104 nt
	global_load_dword v30, v[26:27], off offset:112 nt
	global_load_dword v31, v[26:27], off offset:120 nt
	s_waitcnt vmcnt(3)
	v_mul_f32_e32 v29, v69, v29
	s_waitcnt vmcnt(2)
	v_mul_f32_e32 v32, v70, v32
	ds_write2_b32 v28, v29, v32 offset1:66
	s_waitcnt vmcnt(0)
	v_pk_mul_f32 v[26:27], v[24:25], v[30:31]
	s_cbranch_execnz .LBB0_128

.LBB0_128:
	s_waitcnt vmcnt(17)
	v_add_u32_e32 v24, v34, v48
	ds_write2_b32 v24, v26, v27 offset1:66
	s_and_b64 vcc, exec, s[4:5]
	v_add_u32_e32 v26, v34, v49
	s_cbranch_vccnz .LBB0_143
	s_ashr_i32 s19, s18, 31
	s_waitcnt vmcnt(16)
	v_lshl_add_u64 v[24:25], s[18:19], 0, v[0:1]
	v_lshl_add_u64 v[24:25], v[24:25], 2, s[8:9]
	global_load_dword v27, v[24:25], off offset:128 nt
	global_load_dword v30, v[24:25], off offset:136 nt
	global_load_dword v28, v[24:25], off offset:144 nt
	global_load_dword v29, v[24:25], off offset:152 nt
	s_waitcnt vmcnt(3)
	v_mul_f32_e32 v27, v67, v27
	s_waitcnt vmcnt(2)
	v_mul_f32_e32 v30, v68, v30
	ds_write2_b32 v26, v27, v30 offset1:66
	s_waitcnt vmcnt(0)
	v_pk_mul_f32 v[24:25], v[22:23], v[28:29]
	s_cbranch_execnz .LBB0_131

.LBB0_131:
	s_waitcnt vmcnt(13)
	v_add_u32_e32 v22, v34, v50
	ds_write2_b32 v22, v24, v25 offset1:66
	s_and_b64 vcc, exec, s[4:5]
	v_add_u32_e32 v24, v34, v51
	s_cbranch_vccnz .LBB0_144
	s_ashr_i32 s19, s18, 31
	s_waitcnt vmcnt(12)
	v_lshl_add_u64 v[22:23], s[18:19], 0, v[0:1]
	v_lshl_add_u64 v[22:23], v[22:23], 2, s[8:9]
	global_load_dword v25, v[22:23], off offset:160 nt
	global_load_dword v28, v[22:23], off offset:168 nt
	global_load_dword v26, v[22:23], off offset:176 nt
	global_load_dword v27, v[22:23], off offset:184 nt
	s_waitcnt vmcnt(3)
	v_mul_f32_e32 v25, v65, v25
	s_waitcnt vmcnt(2)
	v_mul_f32_e32 v28, v66, v28
	ds_write2_b32 v24, v25, v28 offset1:66
	s_waitcnt vmcnt(0)
	v_pk_mul_f32 v[22:23], v[20:21], v[26:27]
	s_cbranch_execnz .LBB0_134

.LBB0_134:
	s_waitcnt vmcnt(9)
	v_add_u32_e32 v20, v34, v52
	ds_write2_b32 v20, v22, v23 offset1:66
	s_and_b64 vcc, exec, s[4:5]
	v_add_u32_e32 v22, v34, v53
	s_cbranch_vccnz .LBB0_145
	s_ashr_i32 s19, s18, 31
	s_waitcnt vmcnt(8)
	v_lshl_add_u64 v[20:21], s[18:19], 0, v[0:1]
	v_lshl_add_u64 v[20:21], v[20:21], 2, s[8:9]
	global_load_dword v23, v[20:21], off offset:192 nt
	global_load_dword v26, v[20:21], off offset:200 nt
	global_load_dword v24, v[20:21], off offset:208 nt
	global_load_dword v25, v[20:21], off offset:216 nt
	s_waitcnt vmcnt(3)
	v_mul_f32_e32 v23, v63, v23
	s_waitcnt vmcnt(2)
	v_mul_f32_e32 v26, v64, v26
	ds_write2_b32 v22, v23, v26 offset1:66
	s_waitcnt vmcnt(0)
	v_pk_mul_f32 v[20:21], v[18:19], v[24:25]
	s_cbranch_execnz .LBB0_137

.LBB0_137:
	s_waitcnt vmcnt(8)
	ds_write2_b32 v22, v20, v21 offset0:132 offset1:198
	s_and_b64 vcc, exec, s[4:5]
	v_add_u32_e32 v20, 0x400, v22
	s_cbranch_vccnz .LBB0_146
	s_ashr_i32 s19, s18, 31
	s_waitcnt vmcnt(4)
	v_lshl_add_u64 v[18:19], s[18:19], 0, v[0:1]
	v_lshl_add_u64 v[18:19], v[18:19], 2, s[8:9]
	global_load_dword v21, v[18:19], off offset:224 nt
	global_load_dword v24, v[18:19], off offset:232 nt
	global_load_dword v22, v[18:19], off offset:240 nt
	global_load_dword v23, v[18:19], off offset:248 nt
	s_waitcnt vmcnt(3)
	v_mul_f32_e32 v21, v61, v21
	s_waitcnt vmcnt(2)
	v_mul_f32_e32 v24, v62, v24
	ds_write2_b32 v20, v21, v24 offset0:8 offset1:74
	s_waitcnt vmcnt(0)
	v_pk_mul_f32 v[18:19], v[16:17], v[22:23]
	s_cbranch_execnz .LBB0_19
	s_branch .LBB0_147

.LBB0_174:
	v_add_u32_e32 v0, s8, v0
	global_load_dwordx4 v[6:9], v[2:3], off nt
	v_cmp_lt_i32_e32 vcc, s7, v0
	v_lshl_add_u64 v[2:3], v[2:3], 0, s[10:11]
	s_or_b64 s[16:17], vcc, s[16:17]
	s_waitcnt vmcnt(0)
	v_cvt_pk_bf16_f32 v6, v6, v7
	v_cvt_pk_bf16_f32 v7, v8, v9
	global_store_dwordx2 v[4:5], v[6:7], off
	v_lshl_add_u64 v[4:5], v[4:5], 0, s[14:15]
	s_andn2_b64 exec, exec, s[16:17]
	s_cbranch_execnz .LBB0_174
.LBB0_175:
	s_or_b64 exec, exec, s[4:5]
	s_cmp_lt_i32 s6, 0x8000
	v_mbcnt_lo_u32_b32 v208, -1, 0
	s_cbranch_scc0 .LBB0_182
	s_cmp_eq_u32 s3, 0x100
	s_cbranch_scc1 .Lp0x_fast
	s_load_dwordx4 s[8:11], s[0:1], 0x0
	s_waitcnt lgkmcnt(0)
	s_add_u32 s18, s12, 0x1a00000
	s_addc_u32 s19, s13, 0
	s_add_i32 s4, s2, s6
	v_lshlrev_b32_e32 v80, 4, v174
	v_mov_b32_e32 v81, 0
	s_ashr_i32 s5, s4, 31
	v_lshl_add_u64 v[82:83], s[8:9], 0, v[80:81]
	v_lshl_add_u64 v[84:85], s[10:11], 0, v[80:81]
	s_lshl_b64 s[8:9], s[4:5], 10
	s_ashr_i32 s7, s6, 31
	s_lshl_b64 s[4:5], s[4:5], 12
	v_lshl_add_u64 v[0:1], v[84:85], 0, s[8:9]
	s_lshl_b64 s[8:9], s[6:7], 10
	v_lshl_add_u64 v[24:25], v[82:83], 0, s[4:5]
	s_lshl_b64 s[4:5], s[6:7], 12
	v_lshl_add_u64 v[2:3], v[84:85], 0, s[8:9]
	v_lshl_add_u64 v[32:33], v[82:83], 0, s[4:5]
	global_load_dwordx4 v[4:7], v[0:1], off nt
	global_load_dwordx4 v[20:23], v[2:3], off nt
	s_nop 0
	global_load_dwordx4 v[0:3], v[24:25], off offset:3072 nt
	global_load_dwordx4 v[8:11], v[24:25], off offset:2048 nt
	global_load_dwordx4 v[12:15], v[24:25], off offset:1024 nt
	global_load_dwordx4 v[16:19], v[24:25], off nt
	s_nop 0
	global_load_dwordx4 v[24:27], v[32:33], off offset:3072 nt
	global_load_dwordx4 v[28:31], v[32:33], off offset:2048 nt
	global_load_dwordx4 v[36:39], v[32:33], off offset:1024 nt
	global_load_dwordx4 v[56:59], v[32:33], off nt
	v_mbcnt_hi_u32_b32 v34, -1, v208
	v_and_b32_e32 v32, 64, v34
	v_lshlrev_b32_e32 v80, 3, v174
	v_add_u32_e32 v35, 64, v32
	v_lshl_add_u64 v[32:33], s[12:13], 0, v[80:81]
	s_mov_b64 s[4:5], 0x6800000
	v_lshl_add_u64 v[86:87], v[32:33], 0, s[4:5]
	s_mov_b64 s[4:5], 0xa800000
	v_lshl_add_u64 v[88:89], v[32:33], 0, s[4:5]
	v_xor_b32_e32 v32, 1, v34
	v_cmp_lt_i32_e64 s[4:5], v32, v35
	s_lshl_b32 s8, s3, 4
	s_ashr_i32 s9, s8, 31
	v_cndmask_b32_e64 v32, v34, v32, s[4:5]
	v_lshlrev_b32_e32 v80, 2, v32
	v_xor_b32_e32 v32, 2, v34
	v_cmp_lt_i32_e64 s[4:5], v32, v35
	v_cmp_eq_u32_e32 vcc, 0, v174
	v_mov_b32_e32 v97, 0x358637bd
	v_cndmask_b32_e64 v32, v34, v32, s[4:5]
	v_lshlrev_b32_e32 v92, 2, v32
	v_xor_b32_e32 v32, 4, v34
	v_cmp_lt_i32_e64 s[4:5], v32, v35
	s_mov_b64 s[14:15], s[6:7]
	s_nop 0
	v_cndmask_b32_e64 v32, v34, v32, s[4:5]
	v_lshlrev_b32_e32 v93, 2, v32
	v_xor_b32_e32 v32, 8, v34
	v_cmp_lt_i32_e64 s[4:5], v32, v35
	s_nop 1
	v_cndmask_b32_e64 v32, v34, v32, s[4:5]
	v_lshlrev_b32_e32 v94, 2, v32
	v_xor_b32_e32 v32, 16, v34
	v_cmp_lt_i32_e64 s[4:5], v32, v35
	s_nop 1
	v_cndmask_b32_e64 v32, v34, v32, s[4:5]
	v_lshlrev_b32_e32 v95, 2, v32
	v_xor_b32_e32 v32, 32, v34
	v_cmp_lt_i32_e64 s[4:5], v32, v35
	s_nop 1
	v_cndmask_b32_e64 v32, v34, v32, s[4:5]
	s_lshl_b64 s[4:5], s[6:7], 2
	s_add_u32 s4, s12, s4
	s_addc_u32 s5, s13, s5
	s_add_u32 s4, s4, 0x1a00000
	s_addc_u32 s5, s5, 0
	s_add_i32 s12, s33, s3
	s_lshl_b32 s12, s12, 3
	v_lshlrev_b32_e32 v96, 2, v32
	s_lshl_b64 s[10:11], s[8:9], 2
	s_add_i32 s12, s56, s12
	s_branch .LBB0_178

.LBB0_178:
	s_add_i32 s7, s8, s14
	s_cmp_lt_i32 s7, 0x8000
	s_cselect_b32 s16, s7, s6
	s_ashr_i32 s17, s16, 31
	s_lshl_b64 s[20:21], s[16:17], 12
	v_lshl_add_u64 v[44:45], v[82:83], 0, s[20:21]
	s_lshl_b64 s[20:21], s[16:17], 10
	s_add_i32 s16, s2, s16
	s_ashr_i32 s17, s16, 31
	global_load_dwordx4 v[32:35], v[44:45], off nt
	global_load_dwordx4 v[40:43], v[44:45], off offset:1024 nt
	global_load_dwordx4 v[48:51], v[44:45], off offset:2048 nt
	global_load_dwordx4 v[52:55], v[44:45], off offset:3072 nt
	v_lshl_add_u64 v[44:45], v[84:85], 0, s[20:21]
	s_lshl_b64 s[20:21], s[16:17], 12
	v_lshl_add_u64 v[60:61], v[82:83], 0, s[20:21]
	global_load_dwordx4 v[44:47], v[44:45], off nt
	s_nop 0
	global_load_dwordx4 v[64:67], v[60:61], off nt
	global_load_dwordx4 v[68:71], v[60:61], off offset:1024 nt
	global_load_dwordx4 v[72:75], v[60:61], off offset:2048 nt
	global_load_dwordx4 v[76:79], v[60:61], off offset:3072 nt
	s_lshl_b64 s[16:17], s[16:17], 10
	v_lshl_add_u64 v[60:61], v[84:85], 0, s[16:17]
	global_load_dwordx4 v[60:63], v[60:61], off nt
	s_waitcnt vmcnt(10)
	v_mul_f32_e32 v90, v57, v57
	v_mul_f32_e32 v91, v59, v59
	v_fmac_f32_e32 v90, v56, v56
	v_fmac_f32_e32 v91, v58, v58
	v_add_f32_e32 v90, v90, v91
	v_mul_f32_e32 v91, v37, v37
	v_mul_f32_e32 v98, v39, v39
	v_fmac_f32_e32 v91, v36, v36
	v_fmac_f32_e32 v98, v38, v38
	v_add_f32_e32 v91, v91, v98
	v_add_f32_e32 v90, v90, v91
	v_mul_f32_e32 v91, v29, v29
	v_mul_f32_e32 v98, v31, v31
	v_fmac_f32_e32 v91, v28, v28
	v_fmac_f32_e32 v98, v30, v30
	v_add_f32_e32 v91, v91, v98
	v_add_f32_e32 v90, v90, v91
	v_mul_f32_e32 v91, v25, v25
	v_mul_f32_e32 v98, v27, v27
	v_fmac_f32_e32 v91, v24, v24
	v_fmac_f32_e32 v98, v26, v26
	v_add_f32_e32 v91, v91, v98
	v_add_f32_e32 v90, v90, v91
	v_mul_f32_e32 v91, v17, v17
	v_mul_f32_e32 v98, v19, v19
	v_fmac_f32_e32 v91, v16, v16
	v_fmac_f32_e32 v98, v18, v18
	v_add_f32_e32 v91, v91, v98
	v_mul_f32_e32 v98, v13, v13
	s_waitcnt lgkmcnt(0)
	v_mul_f32_e32 v99, v15, v15
	v_fmac_f32_e32 v98, v12, v12
	v_fmac_f32_e32 v99, v14, v14
	v_add_f32_e32 v98, v98, v99
	v_add_f32_e32 v91, v91, v98
	v_mul_f32_e32 v98, v9, v9
	v_mul_f32_e32 v99, v11, v11
	v_fmac_f32_e32 v98, v8, v8
	v_fmac_f32_e32 v99, v10, v10
	v_add_f32_e32 v98, v98, v99
	v_add_f32_e32 v91, v91, v98
	v_mul_f32_e32 v98, v1, v1
	v_mul_f32_e32 v99, v3, v3
	v_fmac_f32_e32 v98, v0, v0
	v_fmac_f32_e32 v99, v2, v2
	v_add_f32_e32 v98, v98, v99
	v_add_f32_e32 v91, v91, v98
	ds_bpermute_b32 v98, v80, v90
	ds_bpermute_b32 v99, v80, v91
	s_waitcnt lgkmcnt(1)
	v_add_f32_e32 v90, v90, v98
	s_waitcnt lgkmcnt(0)
	v_add_f32_e32 v91, v91, v99
	ds_bpermute_b32 v98, v92, v90
	ds_bpermute_b32 v99, v92, v91
	s_waitcnt lgkmcnt(1)
	v_add_f32_e32 v90, v90, v98
	s_waitcnt lgkmcnt(0)
	v_add_f32_e32 v91, v91, v99
	ds_bpermute_b32 v98, v93, v90
	ds_bpermute_b32 v99, v93, v91
	s_waitcnt lgkmcnt(1)
	v_add_f32_e32 v90, v90, v98
	s_waitcnt lgkmcnt(0)
	v_add_f32_e32 v91, v91, v99
	ds_bpermute_b32 v98, v94, v90
	ds_bpermute_b32 v99, v94, v91
	s_waitcnt lgkmcnt(1)
	v_add_f32_e32 v90, v90, v98
	s_waitcnt lgkmcnt(0)
	v_add_f32_e32 v91, v91, v99
	ds_bpermute_b32 v98, v95, v90
	ds_bpermute_b32 v99, v95, v91
	s_waitcnt lgkmcnt(1)
	v_add_f32_e32 v100, v90, v98
	s_waitcnt lgkmcnt(0)
	v_add_f32_e32 v98, v91, v99
	ds_bpermute_b32 v101, v96, v100
	ds_bpermute_b32 v99, v96, v98
	v_mov_b64_e32 v[90:91], s[14:15]
	s_and_saveexec_b64 s[16:17], vcc
	s_cbranch_execz .LBB0_180
	s_waitcnt lgkmcnt(1)
	v_add_f32_e32 v90, v100, v101
	v_fmamk_f32 v90, v90, 0x3a800000, v97
	v_rsq_f32_e32 v90, v90
	s_bfe_i64 s[20:21], s[14:15], 0x200000
	global_store_dword v81, v90, s[4:5]
	v_mov_b64_e32 v[90:91], s[20:21]

.Lp0x_fast:
	s_load_dwordx4 s[8:11], s[0:1], 0x0
	v_lshlrev_b32_e32 v160, 4, v174
	v_lshlrev_b32_e32 v161, 3, v174
	v_mov_b32_e32 v162, 0
	v_mov_b32_e32 v163, 0x358637bd
	s_lshl_b32 s4, s6, 11
	s_add_u32 s14, s12, s4
	s_addc_u32 s15, s13, 0
	s_add_u32 s14, s14, 0x6800000
	s_addc_u32 s15, s15, 0
	s_lshl_b32 s4, s6, 9
	s_add_u32 s16, s12, s4
	s_addc_u32 s17, s13, 0
	s_add_u32 s16, s16, 0xa800000
	s_addc_u32 s17, s17, 0
	s_lshl_b32 s4, s6, 2
	s_add_u32 s18, s12, s4
	s_addc_u32 s19, s13, 0
	s_add_u32 s18, s18, 0x1a00000
	s_addc_u32 s19, s19, 0
	s_mov_b32 s20, 0
	s_mov_b32 s21, 0x80000000
	s_waitcnt lgkmcnt(0)
	s_lshl_b32 s4, s6, 12
	s_add_u32 s8, s8, s4
	s_addc_u32 s9, s9, 0
	s_lshl_b32 s4, s6, 10
	s_add_u32 s10, s10, s4
	s_addc_u32 s11, s11, 0
	global_load_dwordx4 v[0:3], v160, s[8:9] nt
	global_load_dwordx4 v[4:7], v160, s[8:9] offset:1024 nt
	global_load_dwordx4 v[8:11], v160, s[8:9] offset:2048 nt
	global_load_dwordx4 v[12:15], v160, s[8:9] offset:3072 nt
	global_load_dwordx4 v[16:19], v160, s[10:11] nt
	s_add_u32 s8, s8, 0x800000
	s_addc_u32 s9, s9, 0
	s_add_u32 s10, s10, 0x200000
	s_addc_u32 s11, s11, 0
	global_load_dwordx4 v[20:23], v160, s[8:9] nt
	global_load_dwordx4 v[24:27], v160, s[8:9] offset:1024 nt
	global_load_dwordx4 v[28:31], v160, s[8:9] offset:2048 nt
	global_load_dwordx4 v[32:35], v160, s[8:9] offset:3072 nt
	global_load_dwordx4 v[36:39], v160, s[10:11] nt
	s_add_u32 s8, s8, 0x800000
	s_addc_u32 s9, s9, 0
	s_add_u32 s10, s10, 0x200000
	s_addc_u32 s11, s11, 0
	global_load_dwordx4 v[40:43], v160, s[8:9] nt
	global_load_dwordx4 v[44:47], v160, s[8:9] offset:1024 nt
	global_load_dwordx4 v[48:51], v160, s[8:9] offset:2048 nt
	global_load_dwordx4 v[52:55], v160, s[8:9] offset:3072 nt
	global_load_dwordx4 v[56:59], v160, s[10:11] nt
	s_add_u32 s8, s8, 0x800000
	s_addc_u32 s9, s9, 0
	s_add_u32 s10, s10, 0x200000
	s_addc_u32 s11, s11, 0
	global_load_dwordx4 v[60:63], v160, s[8:9] nt
	global_load_dwordx4 v[64:67], v160, s[8:9] offset:1024 nt
	global_load_dwordx4 v[68:71], v160, s[8:9] offset:2048 nt
	global_load_dwordx4 v[72:75], v160, s[8:9] offset:3072 nt
	global_load_dwordx4 v[76:79], v160, s[10:11] nt
	s_add_u32 s8, s8, 0x800000
	s_addc_u32 s9, s9, 0
	s_add_u32 s10, s10, 0x200000
	s_addc_u32 s11, s11, 0
	global_load_dwordx4 v[80:83], v160, s[8:9] nt
	global_load_dwordx4 v[84:87], v160, s[8:9] offset:1024 nt
	global_load_dwordx4 v[88:91], v160, s[8:9] offset:2048 nt
	global_load_dwordx4 v[92:95], v160, s[8:9] offset:3072 nt
	global_load_dwordx4 v[96:99], v160, s[10:11] nt
	s_add_u32 s8, s8, 0x800000
	s_addc_u32 s9, s9, 0
	s_add_u32 s10, s10, 0x200000
	s_addc_u32 s11, s11, 0
	global_load_dwordx4 v[100:103], v160, s[8:9] nt
	global_load_dwordx4 v[104:107], v160, s[8:9] offset:1024 nt
	global_load_dwordx4 v[108:111], v160, s[8:9] offset:2048 nt
	global_load_dwordx4 v[112:115], v160, s[8:9] offset:3072 nt
	global_load_dwordx4 v[116:119], v160, s[10:11] nt
	s_add_u32 s8, s8, 0x800000
	s_addc_u32 s9, s9, 0
	s_add_u32 s10, s10, 0x200000
	s_addc_u32 s11, s11, 0
	s_waitcnt vmcnt(25)
	v_mul_f32_e32 v164, v1, v1
	v_mul_f32_e32 v168, v3, v3
	v_fmac_f32_e32 v164, v0, v0
	v_fmac_f32_e32 v168, v2, v2
	v_add_f32_e32 v164, v164, v168
	v_mul_f32_e32 v166, v5, v5
	v_mul_f32_e32 v168, v7, v7
	v_fmac_f32_e32 v166, v4, v4
	v_fmac_f32_e32 v168, v6, v6
	v_add_f32_e32 v166, v166, v168
	v_add_f32_e32 v164, v164, v166
	v_mul_f32_e32 v166, v9, v9
	v_mul_f32_e32 v168, v11, v11
	v_fmac_f32_e32 v166, v8, v8
	v_fmac_f32_e32 v168, v10, v10
	v_add_f32_e32 v166, v166, v168
	v_add_f32_e32 v164, v164, v166
	v_mul_f32_e32 v166, v13, v13
	v_mul_f32_e32 v168, v15, v15
	v_fmac_f32_e32 v166, v12, v12
	v_fmac_f32_e32 v168, v14, v14
	v_add_f32_e32 v166, v166, v168
	v_add_f32_e32 v164, v164, v166
	v_cvt_pk_bf16_f32 v180, v0, v1
	v_cvt_pk_bf16_f32 v181, v2, v3
	v_add_f32_dpp v164, v164, v164 quad_perm:[1,0,3,2] row_mask:0xf bank_mask:0xf
	v_cvt_pk_bf16_f32 v182, v4, v5
	v_cvt_pk_bf16_f32 v183, v6, v7
	v_add_f32_dpp v164, v164, v164 quad_perm:[2,3,0,1] row_mask:0xf bank_mask:0xf
	v_cvt_pk_bf16_f32 v184, v8, v9
	v_cvt_pk_bf16_f32 v185, v10, v11
	v_add_f32_dpp v164, v164, v164 row_half_mirror row_mask:0xf bank_mask:0xf
	v_cvt_pk_bf16_f32 v186, v12, v13
	v_cvt_pk_bf16_f32 v187, v14, v15
	v_add_f32_dpp v164, v164, v164 row_mirror row_mask:0xf bank_mask:0xf
	v_cvt_pk_bf16_f32 v188, v16, v17
	v_cvt_pk_bf16_f32 v189, v18, v19
	v_add_f32_dpp v164, v164, v164 row_bcast:15 row_mask:0xa bank_mask:0xf
	s_nop 1
	v_add_f32_dpp v164, v164, v164 row_bcast:31 row_mask:0xc bank_mask:0xf
	global_load_dwordx4 v[0:3], v160, s[8:9] nt
	global_load_dwordx4 v[4:7], v160, s[8:9] offset:1024 nt
	global_load_dwordx4 v[8:11], v160, s[8:9] offset:2048 nt
	global_load_dwordx4 v[12:15], v160, s[8:9] offset:3072 nt
	global_load_dwordx4 v[16:19], v160, s[10:11] nt
	s_add_u32 s8, s8, 0x800000
	s_addc_u32 s9, s9, 0
	s_add_u32 s10, s10, 0x200000
	s_addc_u32 s11, s11, 0
	global_store_dwordx2 v161, v[180:181], s[14:15]
	global_store_dwordx2 v161, v[182:183], s[14:15] offset:512
	global_store_dwordx2 v161, v[184:185], s[14:15] offset:1024
	global_store_dwordx2 v161, v[186:187], s[14:15] offset:1536
	global_store_dwordx2 v161, v[188:189], s[16:17]
	s_add_u32 s14, s14, 0x400000
	s_addc_u32 s15, s15, 0
	s_add_u32 s16, s16, 0x100000
	s_addc_u32 s17, s17, 0
	v_fmamk_f32 v176, v164, 0x3a800000, v163
	v_rsq_f32_e32 v176, v176
	s_mov_b64 exec, s[20:21]
	s_nop 0
	global_store_dword v162, v176, s[18:19]
	s_mov_b64 exec, -1
	s_add_u32 s18, s18, 0x2000
	s_addc_u32 s19, s19, 0
	s_waitcnt vmcnt(31)
	v_mul_f32_e32 v165, v21, v21
	v_mul_f32_e32 v169, v23, v23
	v_fmac_f32_e32 v165, v20, v20
	v_fmac_f32_e32 v169, v22, v22
	v_add_f32_e32 v165, v165, v169
	v_mul_f32_e32 v167, v25, v25
	v_mul_f32_e32 v169, v27, v27
	v_fmac_f32_e32 v167, v24, v24
	v_fmac_f32_e32 v169, v26, v26
	v_add_f32_e32 v167, v167, v169
	v_add_f32_e32 v165, v165, v167
	v_mul_f32_e32 v167, v29, v29
	v_mul_f32_e32 v169, v31, v31
	v_fmac_f32_e32 v167, v28, v28
	v_fmac_f32_e32 v169, v30, v30
	v_add_f32_e32 v167, v167, v169
	v_add_f32_e32 v165, v165, v167
	v_mul_f32_e32 v167, v33, v33
	v_mul_f32_e32 v169, v35, v35
	v_fmac_f32_e32 v167, v32, v32
	v_fmac_f32_e32 v169, v34, v34
	v_add_f32_e32 v167, v167, v169
	v_add_f32_e32 v165, v165, v167
	v_cvt_pk_bf16_f32 v192, v20, v21
	v_cvt_pk_bf16_f32 v193, v22, v23
	v_add_f32_dpp v165, v165, v165 quad_perm:[1,0,3,2] row_mask:0xf bank_mask:0xf
	v_cvt_pk_bf16_f32 v194, v24, v25
	v_cvt_pk_bf16_f32 v195, v26, v27
	v_add_f32_dpp v165, v165, v165 quad_perm:[2,3,0,1] row_mask:0xf bank_mask:0xf
	v_cvt_pk_bf16_f32 v196, v28, v29
	v_cvt_pk_bf16_f32 v197, v30, v31
	v_add_f32_dpp v165, v165, v165 row_half_mirror row_mask:0xf bank_mask:0xf
	v_cvt_pk_bf16_f32 v198, v32, v33
	v_cvt_pk_bf16_f32 v199, v34, v35
	v_add_f32_dpp v165, v165, v165 row_mirror row_mask:0xf bank_mask:0xf
	v_cvt_pk_bf16_f32 v200, v36, v37
	v_cvt_pk_bf16_f32 v201, v38, v39
	v_add_f32_dpp v165, v165, v165 row_bcast:15 row_mask:0xa bank_mask:0xf
	s_nop 1
	v_add_f32_dpp v165, v165, v165 row_bcast:31 row_mask:0xc bank_mask:0xf
	global_load_dwordx4 v[20:23], v160, s[8:9] nt
	global_load_dwordx4 v[24:27], v160, s[8:9] offset:1024 nt
	global_load_dwordx4 v[28:31], v160, s[8:9] offset:2048 nt
	global_load_dwordx4 v[32:35], v160, s[8:9] offset:3072 nt
	global_load_dwordx4 v[36:39], v160, s[10:11] nt
	s_add_u32 s8, s8, 0x800000
	s_addc_u32 s9, s9, 0
	s_add_u32 s10, s10, 0x200000
	s_addc_u32 s11, s11, 0
	global_store_dwordx2 v161, v[192:193], s[14:15]
	global_store_dwordx2 v161, v[194:195], s[14:15] offset:512
	global_store_dwordx2 v161, v[196:197], s[14:15] offset:1024
	global_store_dwordx2 v161, v[198:199], s[14:15] offset:1536
	global_store_dwordx2 v161, v[200:201], s[16:17]
	s_add_u32 s14, s14, 0x400000
	s_addc_u32 s15, s15, 0
	s_add_u32 s16, s16, 0x100000
	s_addc_u32 s17, s17, 0
	v_fmamk_f32 v177, v165, 0x3a800000, v163
	v_rsq_f32_e32 v177, v177
	s_mov_b64 exec, s[20:21]
	s_nop 0
	global_store_dword v162, v177, s[18:19]
	s_mov_b64 exec, -1
	s_add_u32 s18, s18, 0x2000
	s_addc_u32 s19, s19, 0
	s_waitcnt vmcnt(37)
	v_mul_f32_e32 v164, v41, v41
	v_mul_f32_e32 v168, v43, v43
	v_fmac_f32_e32 v164, v40, v40
	v_fmac_f32_e32 v168, v42, v42
	v_add_f32_e32 v164, v164, v168
	v_mul_f32_e32 v166, v45, v45
	v_mul_f32_e32 v168, v47, v47
	v_fmac_f32_e32 v166, v44, v44
	v_fmac_f32_e32 v168, v46, v46
	v_add_f32_e32 v166, v166, v168
	v_add_f32_e32 v164, v164, v166
	v_mul_f32_e32 v166, v49, v49
	v_mul_f32_e32 v168, v51, v51
	v_fmac_f32_e32 v166, v48, v48
	v_fmac_f32_e32 v168, v50, v50
	v_add_f32_e32 v166, v166, v168
	v_add_f32_e32 v164, v164, v166
	v_mul_f32_e32 v166, v53, v53
	v_mul_f32_e32 v168, v55, v55
	v_fmac_f32_e32 v166, v52, v52
	v_fmac_f32_e32 v168, v54, v54
	v_add_f32_e32 v166, v166, v168
	v_add_f32_e32 v164, v164, v166
	v_cvt_pk_bf16_f32 v180, v40, v41
	v_cvt_pk_bf16_f32 v181, v42, v43
	v_add_f32_dpp v164, v164, v164 quad_perm:[1,0,3,2] row_mask:0xf bank_mask:0xf
	v_cvt_pk_bf16_f32 v182, v44, v45
	v_cvt_pk_bf16_f32 v183, v46, v47
	v_add_f32_dpp v164, v164, v164 quad_perm:[2,3,0,1] row_mask:0xf bank_mask:0xf
	v_cvt_pk_bf16_f32 v184, v48, v49
	v_cvt_pk_bf16_f32 v185, v50, v51
	v_add_f32_dpp v164, v164, v164 row_half_mirror row_mask:0xf bank_mask:0xf
	v_cvt_pk_bf16_f32 v186, v52, v53
	v_cvt_pk_bf16_f32 v187, v54, v55
	v_add_f32_dpp v164, v164, v164 row_mirror row_mask:0xf bank_mask:0xf
	v_cvt_pk_bf16_f32 v188, v56, v57
	v_cvt_pk_bf16_f32 v189, v58, v59
	v_add_f32_dpp v164, v164, v164 row_bcast:15 row_mask:0xa bank_mask:0xf
	s_nop 1
	v_add_f32_dpp v164, v164, v164 row_bcast:31 row_mask:0xc bank_mask:0xf
	global_load_dwordx4 v[40:43], v160, s[8:9] nt
	global_load_dwordx4 v[44:47], v160, s[8:9] offset:1024 nt
	global_load_dwordx4 v[48:51], v160, s[8:9] offset:2048 nt
	global_load_dwordx4 v[52:55], v160, s[8:9] offset:3072 nt
	global_load_dwordx4 v[56:59], v160, s[10:11] nt
	s_add_u32 s8, s8, 0x800000
	s_addc_u32 s9, s9, 0
	s_add_u32 s10, s10, 0x200000
	s_addc_u32 s11, s11, 0
	global_store_dwordx2 v161, v[180:181], s[14:15]
	global_store_dwordx2 v161, v[182:183], s[14:15] offset:512
	global_store_dwordx2 v161, v[184:185], s[14:15] offset:1024
	global_store_dwordx2 v161, v[186:187], s[14:15] offset:1536
	global_store_dwordx2 v161, v[188:189], s[16:17]
	s_add_u32 s14, s14, 0x400000
	s_addc_u32 s15, s15, 0
	s_add_u32 s16, s16, 0x100000
	s_addc_u32 s17, s17, 0
	v_fmamk_f32 v176, v164, 0x3a800000, v163
	v_rsq_f32_e32 v176, v176
	s_mov_b64 exec, s[20:21]
	s_nop 0
	global_store_dword v162, v176, s[18:19]
	s_mov_b64 exec, -1
	s_add_u32 s18, s18, 0x2000
	s_addc_u32 s19, s19, 0
	s_waitcnt vmcnt(43)
	v_mul_f32_e32 v165, v61, v61
	v_mul_f32_e32 v169, v63, v63
	v_fmac_f32_e32 v165, v60, v60
	v_fmac_f32_e32 v169, v62, v62
	v_add_f32_e32 v165, v165, v169
	v_mul_f32_e32 v167, v65, v65
	v_mul_f32_e32 v169, v67, v67
	v_fmac_f32_e32 v167, v64, v64
	v_fmac_f32_e32 v169, v66, v66
	v_add_f32_e32 v167, v167, v169
	v_add_f32_e32 v165, v165, v167
	v_mul_f32_e32 v167, v69, v69
	v_mul_f32_e32 v169, v71, v71
	v_fmac_f32_e32 v167, v68, v68
	v_fmac_f32_e32 v169, v70, v70
	v_add_f32_e32 v167, v167, v169
	v_add_f32_e32 v165, v165, v167
	v_mul_f32_e32 v167, v73, v73
	v_mul_f32_e32 v169, v75, v75
	v_fmac_f32_e32 v167, v72, v72
	v_fmac_f32_e32 v169, v74, v74
	v_add_f32_e32 v167, v167, v169
	v_add_f32_e32 v165, v165, v167
	v_cvt_pk_bf16_f32 v192, v60, v61
	v_cvt_pk_bf16_f32 v193, v62, v63
	v_add_f32_dpp v165, v165, v165 quad_perm:[1,0,3,2] row_mask:0xf bank_mask:0xf
	v_cvt_pk_bf16_f32 v194, v64, v65
	v_cvt_pk_bf16_f32 v195, v66, v67
	v_add_f32_dpp v165, v165, v165 quad_perm:[2,3,0,1] row_mask:0xf bank_mask:0xf
	v_cvt_pk_bf16_f32 v196, v68, v69
	v_cvt_pk_bf16_f32 v197, v70, v71
	v_add_f32_dpp v165, v165, v165 row_half_mirror row_mask:0xf bank_mask:0xf
	v_cvt_pk_bf16_f32 v198, v72, v73
	v_cvt_pk_bf16_f32 v199, v74, v75
	v_add_f32_dpp v165, v165, v165 row_mirror row_mask:0xf bank_mask:0xf
	v_cvt_pk_bf16_f32 v200, v76, v77
	v_cvt_pk_bf16_f32 v201, v78, v79
	v_add_f32_dpp v165, v165, v165 row_bcast:15 row_mask:0xa bank_mask:0xf
	s_nop 1
	v_add_f32_dpp v165, v165, v165 row_bcast:31 row_mask:0xc bank_mask:0xf
	global_load_dwordx4 v[60:63], v160, s[8:9] nt
	global_load_dwordx4 v[64:67], v160, s[8:9] offset:1024 nt
	global_load_dwordx4 v[68:71], v160, s[8:9] offset:2048 nt
	global_load_dwordx4 v[72:75], v160, s[8:9] offset:3072 nt
	global_load_dwordx4 v[76:79], v160, s[10:11] nt
	s_add_u32 s8, s8, 0x800000
	s_addc_u32 s9, s9, 0
	s_add_u32 s10, s10, 0x200000
	s_addc_u32 s11, s11, 0
	global_store_dwordx2 v161, v[192:193], s[14:15]
	global_store_dwordx2 v161, v[194:195], s[14:15] offset:512
	global_store_dwordx2 v161, v[196:197], s[14:15] offset:1024
	global_store_dwordx2 v161, v[198:199], s[14:15] offset:1536
	global_store_dwordx2 v161, v[200:201], s[16:17]
	s_add_u32 s14, s14, 0x400000
	s_addc_u32 s15, s15, 0
	s_add_u32 s16, s16, 0x100000
	s_addc_u32 s17, s17, 0
	v_fmamk_f32 v177, v165, 0x3a800000, v163
	v_rsq_f32_e32 v177, v177
	s_mov_b64 exec, s[20:21]
	s_nop 0
	global_store_dword v162, v177, s[18:19]
	s_mov_b64 exec, -1
	s_add_u32 s18, s18, 0x2000
	s_addc_u32 s19, s19, 0
	s_waitcnt vmcnt(49)
	v_mul_f32_e32 v164, v81, v81
	v_mul_f32_e32 v168, v83, v83
	v_fmac_f32_e32 v164, v80, v80
	v_fmac_f32_e32 v168, v82, v82
	v_add_f32_e32 v164, v164, v168
	v_mul_f32_e32 v166, v85, v85
	v_mul_f32_e32 v168, v87, v87
	v_fmac_f32_e32 v166, v84, v84
	v_fmac_f32_e32 v168, v86, v86
	v_add_f32_e32 v166, v166, v168
	v_add_f32_e32 v164, v164, v166
	v_mul_f32_e32 v166, v89, v89
	v_mul_f32_e32 v168, v91, v91
	v_fmac_f32_e32 v166, v88, v88
	v_fmac_f32_e32 v168, v90, v90
	v_add_f32_e32 v166, v166, v168
	v_add_f32_e32 v164, v164, v166
	v_mul_f32_e32 v166, v93, v93
	v_mul_f32_e32 v168, v95, v95
	v_fmac_f32_e32 v166, v92, v92
	v_fmac_f32_e32 v168, v94, v94
	v_add_f32_e32 v166, v166, v168
	v_add_f32_e32 v164, v164, v166
	v_cvt_pk_bf16_f32 v180, v80, v81
	v_cvt_pk_bf16_f32 v181, v82, v83
	v_add_f32_dpp v164, v164, v164 quad_perm:[1,0,3,2] row_mask:0xf bank_mask:0xf
	v_cvt_pk_bf16_f32 v182, v84, v85
	v_cvt_pk_bf16_f32 v183, v86, v87
	v_add_f32_dpp v164, v164, v164 quad_perm:[2,3,0,1] row_mask:0xf bank_mask:0xf
	v_cvt_pk_bf16_f32 v184, v88, v89
	v_cvt_pk_bf16_f32 v185, v90, v91
	v_add_f32_dpp v164, v164, v164 row_half_mirror row_mask:0xf bank_mask:0xf
	v_cvt_pk_bf16_f32 v186, v92, v93
	v_cvt_pk_bf16_f32 v187, v94, v95
	v_add_f32_dpp v164, v164, v164 row_mirror row_mask:0xf bank_mask:0xf
	v_cvt_pk_bf16_f32 v188, v96, v97
	v_cvt_pk_bf16_f32 v189, v98, v99
	v_add_f32_dpp v164, v164, v164 row_bcast:15 row_mask:0xa bank_mask:0xf
	s_nop 1
	v_add_f32_dpp v164, v164, v164 row_bcast:31 row_mask:0xc bank_mask:0xf
	global_load_dwordx4 v[80:83], v160, s[8:9] nt
	global_load_dwordx4 v[84:87], v160, s[8:9] offset:1024 nt
	global_load_dwordx4 v[88:91], v160, s[8:9] offset:2048 nt
	global_load_dwordx4 v[92:95], v160, s[8:9] offset:3072 nt
	global_load_dwordx4 v[96:99], v160, s[10:11] nt
	s_add_u32 s8, s8, 0x800000
	s_addc_u32 s9, s9, 0
	s_add_u32 s10, s10, 0x200000
	s_addc_u32 s11, s11, 0
	global_store_dwordx2 v161, v[180:181], s[14:15]
	global_store_dwordx2 v161, v[182:183], s[14:15] offset:512
	global_store_dwordx2 v161, v[184:185], s[14:15] offset:1024
	global_store_dwordx2 v161, v[186:187], s[14:15] offset:1536
	global_store_dwordx2 v161, v[188:189], s[16:17]
	s_add_u32 s14, s14, 0x400000
	s_addc_u32 s15, s15, 0
	s_add_u32 s16, s16, 0x100000
	s_addc_u32 s17, s17, 0
	v_fmamk_f32 v176, v164, 0x3a800000, v163
	v_rsq_f32_e32 v176, v176
	s_mov_b64 exec, s[20:21]
	s_nop 0
	global_store_dword v162, v176, s[18:19]
	s_mov_b64 exec, -1
	s_add_u32 s18, s18, 0x2000
	s_addc_u32 s19, s19, 0
	s_waitcnt vmcnt(55)
	v_mul_f32_e32 v165, v101, v101
	v_mul_f32_e32 v169, v103, v103
	v_fmac_f32_e32 v165, v100, v100
	v_fmac_f32_e32 v169, v102, v102
	v_add_f32_e32 v165, v165, v169
	v_mul_f32_e32 v167, v105, v105
	v_mul_f32_e32 v169, v107, v107
	v_fmac_f32_e32 v167, v104, v104
	v_fmac_f32_e32 v169, v106, v106
	v_add_f32_e32 v167, v167, v169
	v_add_f32_e32 v165, v165, v167
	v_mul_f32_e32 v167, v109, v109
	v_mul_f32_e32 v169, v111, v111
	v_fmac_f32_e32 v167, v108, v108
	v_fmac_f32_e32 v169, v110, v110
	v_add_f32_e32 v167, v167, v169
	v_add_f32_e32 v165, v165, v167
	v_mul_f32_e32 v167, v113, v113
	v_mul_f32_e32 v169, v115, v115
	v_fmac_f32_e32 v167, v112, v112
	v_fmac_f32_e32 v169, v114, v114
	v_add_f32_e32 v167, v167, v169
	v_add_f32_e32 v165, v165, v167
	v_cvt_pk_bf16_f32 v192, v100, v101
	v_cvt_pk_bf16_f32 v193, v102, v103
	v_add_f32_dpp v165, v165, v165 quad_perm:[1,0,3,2] row_mask:0xf bank_mask:0xf
	v_cvt_pk_bf16_f32 v194, v104, v105
	v_cvt_pk_bf16_f32 v195, v106, v107
	v_add_f32_dpp v165, v165, v165 quad_perm:[2,3,0,1] row_mask:0xf bank_mask:0xf
	v_cvt_pk_bf16_f32 v196, v108, v109
	v_cvt_pk_bf16_f32 v197, v110, v111
	v_add_f32_dpp v165, v165, v165 row_half_mirror row_mask:0xf bank_mask:0xf
	v_cvt_pk_bf16_f32 v198, v112, v113
	v_cvt_pk_bf16_f32 v199, v114, v115
	v_add_f32_dpp v165, v165, v165 row_mirror row_mask:0xf bank_mask:0xf
	v_cvt_pk_bf16_f32 v200, v116, v117
	v_cvt_pk_bf16_f32 v201, v118, v119
	v_add_f32_dpp v165, v165, v165 row_bcast:15 row_mask:0xa bank_mask:0xf
	s_nop 1
	v_add_f32_dpp v165, v165, v165 row_bcast:31 row_mask:0xc bank_mask:0xf
	global_load_dwordx4 v[100:103], v160, s[8:9] nt
	global_load_dwordx4 v[104:107], v160, s[8:9] offset:1024 nt
	global_load_dwordx4 v[108:111], v160, s[8:9] offset:2048 nt
	global_load_dwordx4 v[112:115], v160, s[8:9] offset:3072 nt
	global_load_dwordx4 v[116:119], v160, s[10:11] nt
	s_add_u32 s8, s8, 0x800000
	s_addc_u32 s9, s9, 0
	s_add_u32 s10, s10, 0x200000
	s_addc_u32 s11, s11, 0
	global_store_dwordx2 v161, v[192:193], s[14:15]
	global_store_dwordx2 v161, v[194:195], s[14:15] offset:512
	global_store_dwordx2 v161, v[196:197], s[14:15] offset:1024
	global_store_dwordx2 v161, v[198:199], s[14:15] offset:1536
	global_store_dwordx2 v161, v[200:201], s[16:17]
	s_add_u32 s14, s14, 0x400000
	s_addc_u32 s15, s15, 0
	s_add_u32 s16, s16, 0x100000
	s_addc_u32 s17, s17, 0
	v_fmamk_f32 v177, v165, 0x3a800000, v163
	v_rsq_f32_e32 v177, v177
	s_mov_b64 exec, s[20:21]
	s_nop 0
	global_store_dword v162, v177, s[18:19]
	s_mov_b64 exec, -1
	s_add_u32 s18, s18, 0x2000
	s_addc_u32 s19, s19, 0
	s_waitcnt vmcnt(61)
	v_mul_f32_e32 v164, v1, v1
	v_mul_f32_e32 v168, v3, v3
	v_fmac_f32_e32 v164, v0, v0
	v_fmac_f32_e32 v168, v2, v2
	v_add_f32_e32 v164, v164, v168
	v_mul_f32_e32 v166, v5, v5
	v_mul_f32_e32 v168, v7, v7
	v_fmac_f32_e32 v166, v4, v4
	v_fmac_f32_e32 v168, v6, v6
	v_add_f32_e32 v166, v166, v168
	v_add_f32_e32 v164, v164, v166
	v_mul_f32_e32 v166, v9, v9
	v_mul_f32_e32 v168, v11, v11
	v_fmac_f32_e32 v166, v8, v8
	v_fmac_f32_e32 v168, v10, v10
	v_add_f32_e32 v166, v166, v168
	v_add_f32_e32 v164, v164, v166
	v_mul_f32_e32 v166, v13, v13
	v_mul_f32_e32 v168, v15, v15
	v_fmac_f32_e32 v166, v12, v12
	v_fmac_f32_e32 v168, v14, v14
	v_add_f32_e32 v166, v166, v168
	v_add_f32_e32 v164, v164, v166
	v_cvt_pk_bf16_f32 v180, v0, v1
	v_cvt_pk_bf16_f32 v181, v2, v3
	v_add_f32_dpp v164, v164, v164 quad_perm:[1,0,3,2] row_mask:0xf bank_mask:0xf
	v_cvt_pk_bf16_f32 v182, v4, v5
	v_cvt_pk_bf16_f32 v183, v6, v7
	v_add_f32_dpp v164, v164, v164 quad_perm:[2,3,0,1] row_mask:0xf bank_mask:0xf
	v_cvt_pk_bf16_f32 v184, v8, v9
	v_cvt_pk_bf16_f32 v185, v10, v11
	v_add_f32_dpp v164, v164, v164 row_half_mirror row_mask:0xf bank_mask:0xf
	v_cvt_pk_bf16_f32 v186, v12, v13
	v_cvt_pk_bf16_f32 v187, v14, v15
	v_add_f32_dpp v164, v164, v164 row_mirror row_mask:0xf bank_mask:0xf
	v_cvt_pk_bf16_f32 v188, v16, v17
	v_cvt_pk_bf16_f32 v189, v18, v19
	v_add_f32_dpp v164, v164, v164 row_bcast:15 row_mask:0xa bank_mask:0xf
	s_nop 1
	v_add_f32_dpp v164, v164, v164 row_bcast:31 row_mask:0xc bank_mask:0xf
	global_load_dwordx4 v[0:3], v160, s[8:9] nt
	global_load_dwordx4 v[4:7], v160, s[8:9] offset:1024 nt
	global_load_dwordx4 v[8:11], v160, s[8:9] offset:2048 nt
	global_load_dwordx4 v[12:15], v160, s[8:9] offset:3072 nt
	global_load_dwordx4 v[16:19], v160, s[10:11] nt
	s_add_u32 s8, s8, 0x800000
	s_addc_u32 s9, s9, 0
	s_add_u32 s10, s10, 0x200000
	s_addc_u32 s11, s11, 0
	global_store_dwordx2 v161, v[180:181], s[14:15]
	global_store_dwordx2 v161, v[182:183], s[14:15] offset:512
	global_store_dwordx2 v161, v[184:185], s[14:15] offset:1024
	global_store_dwordx2 v161, v[186:187], s[14:15] offset:1536
	global_store_dwordx2 v161, v[188:189], s[16:17]
	s_add_u32 s14, s14, 0x400000
	s_addc_u32 s15, s15, 0
	s_add_u32 s16, s16, 0x100000
	s_addc_u32 s17, s17, 0
	v_fmamk_f32 v176, v164, 0x3a800000, v163
	v_rsq_f32_e32 v176, v176
	s_mov_b64 exec, s[20:21]
	s_nop 0
	global_store_dword v162, v176, s[18:19]
	s_mov_b64 exec, -1
	s_add_u32 s18, s18, 0x2000
	s_addc_u32 s19, s19, 0
	s_waitcnt vmcnt(61)
	v_mul_f32_e32 v165, v21, v21
	v_mul_f32_e32 v169, v23, v23
	v_fmac_f32_e32 v165, v20, v20
	v_fmac_f32_e32 v169, v22, v22
	v_add_f32_e32 v165, v165, v169
	v_mul_f32_e32 v167, v25, v25
	v_mul_f32_e32 v169, v27, v27
	v_fmac_f32_e32 v167, v24, v24
	v_fmac_f32_e32 v169, v26, v26
	v_add_f32_e32 v167, v167, v169
	v_add_f32_e32 v165, v165, v167
	v_mul_f32_e32 v167, v29, v29
	v_mul_f32_e32 v169, v31, v31
	v_fmac_f32_e32 v167, v28, v28
	v_fmac_f32_e32 v169, v30, v30
	v_add_f32_e32 v167, v167, v169
	v_add_f32_e32 v165, v165, v167
	v_mul_f32_e32 v167, v33, v33
	v_mul_f32_e32 v169, v35, v35
	v_fmac_f32_e32 v167, v32, v32
	v_fmac_f32_e32 v169, v34, v34
	v_add_f32_e32 v167, v167, v169
	v_add_f32_e32 v165, v165, v167
	v_cvt_pk_bf16_f32 v192, v20, v21
	v_cvt_pk_bf16_f32 v193, v22, v23
	v_add_f32_dpp v165, v165, v165 quad_perm:[1,0,3,2] row_mask:0xf bank_mask:0xf
	v_cvt_pk_bf16_f32 v194, v24, v25
	v_cvt_pk_bf16_f32 v195, v26, v27
	v_add_f32_dpp v165, v165, v165 quad_perm:[2,3,0,1] row_mask:0xf bank_mask:0xf
	v_cvt_pk_bf16_f32 v196, v28, v29
	v_cvt_pk_bf16_f32 v197, v30, v31
	v_add_f32_dpp v165, v165, v165 row_half_mirror row_mask:0xf bank_mask:0xf
	v_cvt_pk_bf16_f32 v198, v32, v33
	v_cvt_pk_bf16_f32 v199, v34, v35
	v_add_f32_dpp v165, v165, v165 row_mirror row_mask:0xf bank_mask:0xf
	v_cvt_pk_bf16_f32 v200, v36, v37
	v_cvt_pk_bf16_f32 v201, v38, v39
	v_add_f32_dpp v165, v165, v165 row_bcast:15 row_mask:0xa bank_mask:0xf
	s_nop 1
	v_add_f32_dpp v165, v165, v165 row_bcast:31 row_mask:0xc bank_mask:0xf
	global_load_dwordx4 v[20:23], v160, s[8:9] nt
	global_load_dwordx4 v[24:27], v160, s[8:9] offset:1024 nt
	global_load_dwordx4 v[28:31], v160, s[8:9] offset:2048 nt
	global_load_dwordx4 v[32:35], v160, s[8:9] offset:3072 nt
	global_load_dwordx4 v[36:39], v160, s[10:11] nt
	s_add_u32 s8, s8, 0x800000
	s_addc_u32 s9, s9, 0
	s_add_u32 s10, s10, 0x200000
	s_addc_u32 s11, s11, 0
	global_store_dwordx2 v161, v[192:193], s[14:15]
	global_store_dwordx2 v161, v[194:195], s[14:15] offset:512
	global_store_dwordx2 v161, v[196:197], s[14:15] offset:1024
	global_store_dwordx2 v161, v[198:199], s[14:15] offset:1536
	global_store_dwordx2 v161, v[200:201], s[16:17]
	s_add_u32 s14, s14, 0x400000
	s_addc_u32 s15, s15, 0
	s_add_u32 s16, s16, 0x100000
	s_addc_u32 s17, s17, 0
	v_fmamk_f32 v177, v165, 0x3a800000, v163
	v_rsq_f32_e32 v177, v177
	s_mov_b64 exec, s[20:21]
	s_nop 0
	global_store_dword v162, v177, s[18:19]
	s_mov_b64 exec, -1
	s_add_u32 s18, s18, 0x2000
	s_addc_u32 s19, s19, 0
	s_waitcnt vmcnt(61)
	v_mul_f32_e32 v164, v41, v41
	v_mul_f32_e32 v168, v43, v43
	v_fmac_f32_e32 v164, v40, v40
	v_fmac_f32_e32 v168, v42, v42
	v_add_f32_e32 v164, v164, v168
	v_mul_f32_e32 v166, v45, v45
	v_mul_f32_e32 v168, v47, v47
	v_fmac_f32_e32 v166, v44, v44
	v_fmac_f32_e32 v168, v46, v46
	v_add_f32_e32 v166, v166, v168
	v_add_f32_e32 v164, v164, v166
	v_mul_f32_e32 v166, v49, v49
	v_mul_f32_e32 v168, v51, v51
	v_fmac_f32_e32 v166, v48, v48
	v_fmac_f32_e32 v168, v50, v50
	v_add_f32_e32 v166, v166, v168
	v_add_f32_e32 v164, v164, v166
	v_mul_f32_e32 v166, v53, v53
	v_mul_f32_e32 v168, v55, v55
	v_fmac_f32_e32 v166, v52, v52
	v_fmac_f32_e32 v168, v54, v54
	v_add_f32_e32 v166, v166, v168
	v_add_f32_e32 v164, v164, v166
	v_cvt_pk_bf16_f32 v180, v40, v41
	v_cvt_pk_bf16_f32 v181, v42, v43
	v_add_f32_dpp v164, v164, v164 quad_perm:[1,0,3,2] row_mask:0xf bank_mask:0xf
	v_cvt_pk_bf16_f32 v182, v44, v45
	v_cvt_pk_bf16_f32 v183, v46, v47
	v_add_f32_dpp v164, v164, v164 quad_perm:[2,3,0,1] row_mask:0xf bank_mask:0xf
	v_cvt_pk_bf16_f32 v184, v48, v49
	v_cvt_pk_bf16_f32 v185, v50, v51
	v_add_f32_dpp v164, v164, v164 row_half_mirror row_mask:0xf bank_mask:0xf
	v_cvt_pk_bf16_f32 v186, v52, v53
	v_cvt_pk_bf16_f32 v187, v54, v55
	v_add_f32_dpp v164, v164, v164 row_mirror row_mask:0xf bank_mask:0xf
	v_cvt_pk_bf16_f32 v188, v56, v57
	v_cvt_pk_bf16_f32 v189, v58, v59
	v_add_f32_dpp v164, v164, v164 row_bcast:15 row_mask:0xa bank_mask:0xf
	s_nop 1
	v_add_f32_dpp v164, v164, v164 row_bcast:31 row_mask:0xc bank_mask:0xf
	global_load_dwordx4 v[40:43], v160, s[8:9] nt
	global_load_dwordx4 v[44:47], v160, s[8:9] offset:1024 nt
	global_load_dwordx4 v[48:51], v160, s[8:9] offset:2048 nt
	global_load_dwordx4 v[52:55], v160, s[8:9] offset:3072 nt
	global_load_dwordx4 v[56:59], v160, s[10:11] nt
	s_add_u32 s8, s8, 0x800000
	s_addc_u32 s9, s9, 0
	s_add_u32 s10, s10, 0x200000
	s_addc_u32 s11, s11, 0
	global_store_dwordx2 v161, v[180:181], s[14:15]
	global_store_dwordx2 v161, v[182:183], s[14:15] offset:512
	global_store_dwordx2 v161, v[184:185], s[14:15] offset:1024
	global_store_dwordx2 v161, v[186:187], s[14:15] offset:1536
	global_store_dwordx2 v161, v[188:189], s[16:17]
	s_add_u32 s14, s14, 0x400000
	s_addc_u32 s15, s15, 0
	s_add_u32 s16, s16, 0x100000
	s_addc_u32 s17, s17, 0
	v_fmamk_f32 v176, v164, 0x3a800000, v163
	v_rsq_f32_e32 v176, v176
	s_mov_b64 exec, s[20:21]
	s_nop 0
	global_store_dword v162, v176, s[18:19]
	s_mov_b64 exec, -1
	s_add_u32 s18, s18, 0x2000
	s_addc_u32 s19, s19, 0
	s_waitcnt vmcnt(61)
	v_mul_f32_e32 v165, v61, v61
	v_mul_f32_e32 v169, v63, v63
	v_fmac_f32_e32 v165, v60, v60
	v_fmac_f32_e32 v169, v62, v62
	v_add_f32_e32 v165, v165, v169
	v_mul_f32_e32 v167, v65, v65
	v_mul_f32_e32 v169, v67, v67
	v_fmac_f32_e32 v167, v64, v64
	v_fmac_f32_e32 v169, v66, v66
	v_add_f32_e32 v167, v167, v169
	v_add_f32_e32 v165, v165, v167
	v_mul_f32_e32 v167, v69, v69
	v_mul_f32_e32 v169, v71, v71
	v_fmac_f32_e32 v167, v68, v68
	v_fmac_f32_e32 v169, v70, v70
	v_add_f32_e32 v167, v167, v169
	v_add_f32_e32 v165, v165, v167
	v_mul_f32_e32 v167, v73, v73
	v_mul_f32_e32 v169, v75, v75
	v_fmac_f32_e32 v167, v72, v72
	v_fmac_f32_e32 v169, v74, v74
	v_add_f32_e32 v167, v167, v169
	v_add_f32_e32 v165, v165, v167
	v_cvt_pk_bf16_f32 v192, v60, v61
	v_cvt_pk_bf16_f32 v193, v62, v63
	v_add_f32_dpp v165, v165, v165 quad_perm:[1,0,3,2] row_mask:0xf bank_mask:0xf
	v_cvt_pk_bf16_f32 v194, v64, v65
	v_cvt_pk_bf16_f32 v195, v66, v67
	v_add_f32_dpp v165, v165, v165 quad_perm:[2,3,0,1] row_mask:0xf bank_mask:0xf
	v_cvt_pk_bf16_f32 v196, v68, v69
	v_cvt_pk_bf16_f32 v197, v70, v71
	v_add_f32_dpp v165, v165, v165 row_half_mirror row_mask:0xf bank_mask:0xf
	v_cvt_pk_bf16_f32 v198, v72, v73
	v_cvt_pk_bf16_f32 v199, v74, v75
	v_add_f32_dpp v165, v165, v165 row_mirror row_mask:0xf bank_mask:0xf
	v_cvt_pk_bf16_f32 v200, v76, v77
	v_cvt_pk_bf16_f32 v201, v78, v79
	v_add_f32_dpp v165, v165, v165 row_bcast:15 row_mask:0xa bank_mask:0xf
	s_nop 1
	v_add_f32_dpp v165, v165, v165 row_bcast:31 row_mask:0xc bank_mask:0xf
	global_load_dwordx4 v[60:63], v160, s[8:9] nt
	global_load_dwordx4 v[64:67], v160, s[8:9] offset:1024 nt
	global_load_dwordx4 v[68:71], v160, s[8:9] offset:2048 nt
	global_load_dwordx4 v[72:75], v160, s[8:9] offset:3072 nt
	global_load_dwordx4 v[76:79], v160, s[10:11] nt
	s_add_u32 s8, s8, 0x800000
	s_addc_u32 s9, s9, 0
	s_add_u32 s10, s10, 0x200000
	s_addc_u32 s11, s11, 0
	global_store_dwordx2 v161, v[192:193], s[14:15]
	global_store_dwordx2 v161, v[194:195], s[14:15] offset:512
	global_store_dwordx2 v161, v[196:197], s[14:15] offset:1024
	global_store_dwordx2 v161, v[198:199], s[14:15] offset:1536
	global_store_dwordx2 v161, v[200:201], s[16:17]
	s_add_u32 s14, s14, 0x400000
	s_addc_u32 s15, s15, 0
	s_add_u32 s16, s16, 0x100000
	s_addc_u32 s17, s17, 0
	v_fmamk_f32 v177, v165, 0x3a800000, v163
	v_rsq_f32_e32 v177, v177
	s_mov_b64 exec, s[20:21]
	s_nop 0
	global_store_dword v162, v177, s[18:19]
	s_mov_b64 exec, -1
	s_add_u32 s18, s18, 0x2000
	s_addc_u32 s19, s19, 0
	s_waitcnt vmcnt(61)
	v_mul_f32_e32 v164, v81, v81
	v_mul_f32_e32 v168, v83, v83
	v_fmac_f32_e32 v164, v80, v80
	v_fmac_f32_e32 v168, v82, v82
	v_add_f32_e32 v164, v164, v168
	v_mul_f32_e32 v166, v85, v85
	v_mul_f32_e32 v168, v87, v87
	v_fmac_f32_e32 v166, v84, v84
	v_fmac_f32_e32 v168, v86, v86
	v_add_f32_e32 v166, v166, v168
	v_add_f32_e32 v164, v164, v166
	v_mul_f32_e32 v166, v89, v89
	v_mul_f32_e32 v168, v91, v91
	v_fmac_f32_e32 v166, v88, v88
	v_fmac_f32_e32 v168, v90, v90
	v_add_f32_e32 v166, v166, v168
	v_add_f32_e32 v164, v164, v166
	v_mul_f32_e32 v166, v93, v93
	v_mul_f32_e32 v168, v95, v95
	v_fmac_f32_e32 v166, v92, v92
	v_fmac_f32_e32 v168, v94, v94
	v_add_f32_e32 v166, v166, v168
	v_add_f32_e32 v164, v164, v166
	v_cvt_pk_bf16_f32 v180, v80, v81
	v_cvt_pk_bf16_f32 v181, v82, v83
	v_add_f32_dpp v164, v164, v164 quad_perm:[1,0,3,2] row_mask:0xf bank_mask:0xf
	v_cvt_pk_bf16_f32 v182, v84, v85
	v_cvt_pk_bf16_f32 v183, v86, v87
	v_add_f32_dpp v164, v164, v164 quad_perm:[2,3,0,1] row_mask:0xf bank_mask:0xf
	v_cvt_pk_bf16_f32 v184, v88, v89
	v_cvt_pk_bf16_f32 v185, v90, v91
	v_add_f32_dpp v164, v164, v164 row_half_mirror row_mask:0xf bank_mask:0xf
	v_cvt_pk_bf16_f32 v186, v92, v93
	v_cvt_pk_bf16_f32 v187, v94, v95
	v_add_f32_dpp v164, v164, v164 row_mirror row_mask:0xf bank_mask:0xf
	v_cvt_pk_bf16_f32 v188, v96, v97
	v_cvt_pk_bf16_f32 v189, v98, v99
	v_add_f32_dpp v164, v164, v164 row_bcast:15 row_mask:0xa bank_mask:0xf
	s_nop 1
	v_add_f32_dpp v164, v164, v164 row_bcast:31 row_mask:0xc bank_mask:0xf
	global_store_dwordx2 v161, v[180:181], s[14:15]
	global_store_dwordx2 v161, v[182:183], s[14:15] offset:512
	global_store_dwordx2 v161, v[184:185], s[14:15] offset:1024
	global_store_dwordx2 v161, v[186:187], s[14:15] offset:1536
	global_store_dwordx2 v161, v[188:189], s[16:17]
	s_add_u32 s14, s14, 0x400000
	s_addc_u32 s15, s15, 0
	s_add_u32 s16, s16, 0x100000
	s_addc_u32 s17, s17, 0
	v_fmamk_f32 v176, v164, 0x3a800000, v163
	v_rsq_f32_e32 v176, v176
	s_mov_b64 exec, s[20:21]
	s_nop 0
	global_store_dword v162, v176, s[18:19]
	s_mov_b64 exec, -1
	s_add_u32 s18, s18, 0x2000
	s_addc_u32 s19, s19, 0
	s_waitcnt vmcnt(56)
	v_mul_f32_e32 v165, v101, v101
	v_mul_f32_e32 v169, v103, v103
	v_fmac_f32_e32 v165, v100, v100
	v_fmac_f32_e32 v169, v102, v102
	v_add_f32_e32 v165, v165, v169
	v_mul_f32_e32 v167, v105, v105
	v_mul_f32_e32 v169, v107, v107
	v_fmac_f32_e32 v167, v104, v104
	v_fmac_f32_e32 v169, v106, v106
	v_add_f32_e32 v167, v167, v169
	v_add_f32_e32 v165, v165, v167
	v_mul_f32_e32 v167, v109, v109
	v_mul_f32_e32 v169, v111, v111
	v_fmac_f32_e32 v167, v108, v108
	v_fmac_f32_e32 v169, v110, v110
	v_add_f32_e32 v167, v167, v169
	v_add_f32_e32 v165, v165, v167
	v_mul_f32_e32 v167, v113, v113
	v_mul_f32_e32 v169, v115, v115
	v_fmac_f32_e32 v167, v112, v112
	v_fmac_f32_e32 v169, v114, v114
	v_add_f32_e32 v167, v167, v169
	v_add_f32_e32 v165, v165, v167
	v_cvt_pk_bf16_f32 v192, v100, v101
	v_cvt_pk_bf16_f32 v193, v102, v103
	v_add_f32_dpp v165, v165, v165 quad_perm:[1,0,3,2] row_mask:0xf bank_mask:0xf
	v_cvt_pk_bf16_f32 v194, v104, v105
	v_cvt_pk_bf16_f32 v195, v106, v107
	v_add_f32_dpp v165, v165, v165 quad_perm:[2,3,0,1] row_mask:0xf bank_mask:0xf
	v_cvt_pk_bf16_f32 v196, v108, v109
	v_cvt_pk_bf16_f32 v197, v110, v111
	v_add_f32_dpp v165, v165, v165 row_half_mirror row_mask:0xf bank_mask:0xf
	v_cvt_pk_bf16_f32 v198, v112, v113
	v_cvt_pk_bf16_f32 v199, v114, v115
	v_add_f32_dpp v165, v165, v165 row_mirror row_mask:0xf bank_mask:0xf
	v_cvt_pk_bf16_f32 v200, v116, v117
	v_cvt_pk_bf16_f32 v201, v118, v119
	v_add_f32_dpp v165, v165, v165 row_bcast:15 row_mask:0xa bank_mask:0xf
	s_nop 1
	v_add_f32_dpp v165, v165, v165 row_bcast:31 row_mask:0xc bank_mask:0xf
	global_store_dwordx2 v161, v[192:193], s[14:15]
	global_store_dwordx2 v161, v[194:195], s[14:15] offset:512
	global_store_dwordx2 v161, v[196:197], s[14:15] offset:1024
	global_store_dwordx2 v161, v[198:199], s[14:15] offset:1536
	global_store_dwordx2 v161, v[200:201], s[16:17]
	s_add_u32 s14, s14, 0x400000
	s_addc_u32 s15, s15, 0
	s_add_u32 s16, s16, 0x100000
	s_addc_u32 s17, s17, 0
	v_fmamk_f32 v177, v165, 0x3a800000, v163
	v_rsq_f32_e32 v177, v177
	s_mov_b64 exec, s[20:21]
	s_nop 0
	global_store_dword v162, v177, s[18:19]
	s_mov_b64 exec, -1
	s_add_u32 s18, s18, 0x2000
	s_addc_u32 s19, s19, 0
	s_waitcnt vmcnt(51)
	v_mul_f32_e32 v164, v1, v1
	v_mul_f32_e32 v168, v3, v3
	v_fmac_f32_e32 v164, v0, v0
	v_fmac_f32_e32 v168, v2, v2
	v_add_f32_e32 v164, v164, v168
	v_mul_f32_e32 v166, v5, v5
	v_mul_f32_e32 v168, v7, v7
	v_fmac_f32_e32 v166, v4, v4
	v_fmac_f32_e32 v168, v6, v6
	v_add_f32_e32 v166, v166, v168
	v_add_f32_e32 v164, v164, v166
	v_mul_f32_e32 v166, v9, v9
	v_mul_f32_e32 v168, v11, v11
	v_fmac_f32_e32 v166, v8, v8
	v_fmac_f32_e32 v168, v10, v10
	v_add_f32_e32 v166, v166, v168
	v_add_f32_e32 v164, v164, v166
	v_mul_f32_e32 v166, v13, v13
	v_mul_f32_e32 v168, v15, v15
	v_fmac_f32_e32 v166, v12, v12
	v_fmac_f32_e32 v168, v14, v14
	v_add_f32_e32 v166, v166, v168
	v_add_f32_e32 v164, v164, v166
	v_cvt_pk_bf16_f32 v180, v0, v1
	v_cvt_pk_bf16_f32 v181, v2, v3
	v_add_f32_dpp v164, v164, v164 quad_perm:[1,0,3,2] row_mask:0xf bank_mask:0xf
	v_cvt_pk_bf16_f32 v182, v4, v5
	v_cvt_pk_bf16_f32 v183, v6, v7
	v_add_f32_dpp v164, v164, v164 quad_perm:[2,3,0,1] row_mask:0xf bank_mask:0xf
	v_cvt_pk_bf16_f32 v184, v8, v9
	v_cvt_pk_bf16_f32 v185, v10, v11
	v_add_f32_dpp v164, v164, v164 row_half_mirror row_mask:0xf bank_mask:0xf
	v_cvt_pk_bf16_f32 v186, v12, v13
	v_cvt_pk_bf16_f32 v187, v14, v15
	v_add_f32_dpp v164, v164, v164 row_mirror row_mask:0xf bank_mask:0xf
	v_cvt_pk_bf16_f32 v188, v16, v17
	v_cvt_pk_bf16_f32 v189, v18, v19
	v_add_f32_dpp v164, v164, v164 row_bcast:15 row_mask:0xa bank_mask:0xf
	s_nop 1
	v_add_f32_dpp v164, v164, v164 row_bcast:31 row_mask:0xc bank_mask:0xf
	global_store_dwordx2 v161, v[180:181], s[14:15]
	global_store_dwordx2 v161, v[182:183], s[14:15] offset:512
	global_store_dwordx2 v161, v[184:185], s[14:15] offset:1024
	global_store_dwordx2 v161, v[186:187], s[14:15] offset:1536
	global_store_dwordx2 v161, v[188:189], s[16:17]
	s_add_u32 s14, s14, 0x400000
	s_addc_u32 s15, s15, 0
	s_add_u32 s16, s16, 0x100000
	s_addc_u32 s17, s17, 0
	v_fmamk_f32 v176, v164, 0x3a800000, v163
	v_rsq_f32_e32 v176, v176
	s_mov_b64 exec, s[20:21]
	s_nop 0
	global_store_dword v162, v176, s[18:19]
	s_mov_b64 exec, -1
	s_add_u32 s18, s18, 0x2000
	s_addc_u32 s19, s19, 0
	s_waitcnt vmcnt(46)
	v_mul_f32_e32 v165, v21, v21
	v_mul_f32_e32 v169, v23, v23
	v_fmac_f32_e32 v165, v20, v20
	v_fmac_f32_e32 v169, v22, v22
	v_add_f32_e32 v165, v165, v169
	v_mul_f32_e32 v167, v25, v25
	v_mul_f32_e32 v169, v27, v27
	v_fmac_f32_e32 v167, v24, v24
	v_fmac_f32_e32 v169, v26, v26
	v_add_f32_e32 v167, v167, v169
	v_add_f32_e32 v165, v165, v167
	v_mul_f32_e32 v167, v29, v29
	v_mul_f32_e32 v169, v31, v31
	v_fmac_f32_e32 v167, v28, v28
	v_fmac_f32_e32 v169, v30, v30
	v_add_f32_e32 v167, v167, v169
	v_add_f32_e32 v165, v165, v167
	v_mul_f32_e32 v167, v33, v33
	v_mul_f32_e32 v169, v35, v35
	v_fmac_f32_e32 v167, v32, v32
	v_fmac_f32_e32 v169, v34, v34
	v_add_f32_e32 v167, v167, v169
	v_add_f32_e32 v165, v165, v167
	v_cvt_pk_bf16_f32 v192, v20, v21
	v_cvt_pk_bf16_f32 v193, v22, v23
	v_add_f32_dpp v165, v165, v165 quad_perm:[1,0,3,2] row_mask:0xf bank_mask:0xf
	v_cvt_pk_bf16_f32 v194, v24, v25
	v_cvt_pk_bf16_f32 v195, v26, v27
	v_add_f32_dpp v165, v165, v165 quad_perm:[2,3,0,1] row_mask:0xf bank_mask:0xf
	v_cvt_pk_bf16_f32 v196, v28, v29
	v_cvt_pk_bf16_f32 v197, v30, v31
	v_add_f32_dpp v165, v165, v165 row_half_mirror row_mask:0xf bank_mask:0xf
	v_cvt_pk_bf16_f32 v198, v32, v33
	v_cvt_pk_bf16_f32 v199, v34, v35
	v_add_f32_dpp v165, v165, v165 row_mirror row_mask:0xf bank_mask:0xf
	v_cvt_pk_bf16_f32 v200, v36, v37
	v_cvt_pk_bf16_f32 v201, v38, v39
	v_add_f32_dpp v165, v165, v165 row_bcast:15 row_mask:0xa bank_mask:0xf
	s_nop 1
	v_add_f32_dpp v165, v165, v165 row_bcast:31 row_mask:0xc bank_mask:0xf
	global_store_dwordx2 v161, v[192:193], s[14:15]
	global_store_dwordx2 v161, v[194:195], s[14:15] offset:512
	global_store_dwordx2 v161, v[196:197], s[14:15] offset:1024
	global_store_dwordx2 v161, v[198:199], s[14:15] offset:1536
	global_store_dwordx2 v161, v[200:201], s[16:17]
	s_add_u32 s14, s14, 0x400000
	s_addc_u32 s15, s15, 0
	s_add_u32 s16, s16, 0x100000
	s_addc_u32 s17, s17, 0
	v_fmamk_f32 v177, v165, 0x3a800000, v163
	v_rsq_f32_e32 v177, v177
	s_mov_b64 exec, s[20:21]
	s_nop 0
	global_store_dword v162, v177, s[18:19]
	s_mov_b64 exec, -1
	s_add_u32 s18, s18, 0x2000
	s_addc_u32 s19, s19, 0
	s_waitcnt vmcnt(41)
	v_mul_f32_e32 v164, v41, v41
	v_mul_f32_e32 v168, v43, v43
	v_fmac_f32_e32 v164, v40, v40
	v_fmac_f32_e32 v168, v42, v42
	v_add_f32_e32 v164, v164, v168
	v_mul_f32_e32 v166, v45, v45
	v_mul_f32_e32 v168, v47, v47
	v_fmac_f32_e32 v166, v44, v44
	v_fmac_f32_e32 v168, v46, v46
	v_add_f32_e32 v166, v166, v168
	v_add_f32_e32 v164, v164, v166
	v_mul_f32_e32 v166, v49, v49
	v_mul_f32_e32 v168, v51, v51
	v_fmac_f32_e32 v166, v48, v48
	v_fmac_f32_e32 v168, v50, v50
	v_add_f32_e32 v166, v166, v168
	v_add_f32_e32 v164, v164, v166
	v_mul_f32_e32 v166, v53, v53
	v_mul_f32_e32 v168, v55, v55
	v_fmac_f32_e32 v166, v52, v52
	v_fmac_f32_e32 v168, v54, v54
	v_add_f32_e32 v166, v166, v168
	v_add_f32_e32 v164, v164, v166
	v_cvt_pk_bf16_f32 v180, v40, v41
	v_cvt_pk_bf16_f32 v181, v42, v43
	v_add_f32_dpp v164, v164, v164 quad_perm:[1,0,3,2] row_mask:0xf bank_mask:0xf
	v_cvt_pk_bf16_f32 v182, v44, v45
	v_cvt_pk_bf16_f32 v183, v46, v47
	v_add_f32_dpp v164, v164, v164 quad_perm:[2,3,0,1] row_mask:0xf bank_mask:0xf
	v_cvt_pk_bf16_f32 v184, v48, v49
	v_cvt_pk_bf16_f32 v185, v50, v51
	v_add_f32_dpp v164, v164, v164 row_half_mirror row_mask:0xf bank_mask:0xf
	v_cvt_pk_bf16_f32 v186, v52, v53
	v_cvt_pk_bf16_f32 v187, v54, v55
	v_add_f32_dpp v164, v164, v164 row_mirror row_mask:0xf bank_mask:0xf
	v_cvt_pk_bf16_f32 v188, v56, v57
	v_cvt_pk_bf16_f32 v189, v58, v59
	v_add_f32_dpp v164, v164, v164 row_bcast:15 row_mask:0xa bank_mask:0xf
	s_nop 1
	v_add_f32_dpp v164, v164, v164 row_bcast:31 row_mask:0xc bank_mask:0xf
	global_store_dwordx2 v161, v[180:181], s[14:15]
	global_store_dwordx2 v161, v[182:183], s[14:15] offset:512
	global_store_dwordx2 v161, v[184:185], s[14:15] offset:1024
	global_store_dwordx2 v161, v[186:187], s[14:15] offset:1536
	global_store_dwordx2 v161, v[188:189], s[16:17]
	s_add_u32 s14, s14, 0x400000
	s_addc_u32 s15, s15, 0
	s_add_u32 s16, s16, 0x100000
	s_addc_u32 s17, s17, 0
	v_fmamk_f32 v176, v164, 0x3a800000, v163
	v_rsq_f32_e32 v176, v176
	s_mov_b64 exec, s[20:21]
	s_nop 0
	global_store_dword v162, v176, s[18:19]
	s_mov_b64 exec, -1
	s_add_u32 s18, s18, 0x2000
	s_addc_u32 s19, s19, 0
	s_waitcnt vmcnt(36)
	v_mul_f32_e32 v165, v61, v61
	v_mul_f32_e32 v169, v63, v63
	v_fmac_f32_e32 v165, v60, v60
	v_fmac_f32_e32 v169, v62, v62
	v_add_f32_e32 v165, v165, v169
	v_mul_f32_e32 v167, v65, v65
	v_mul_f32_e32 v169, v67, v67
	v_fmac_f32_e32 v167, v64, v64
	v_fmac_f32_e32 v169, v66, v66
	v_add_f32_e32 v167, v167, v169
	v_add_f32_e32 v165, v165, v167
	v_mul_f32_e32 v167, v69, v69
	v_mul_f32_e32 v169, v71, v71
	v_fmac_f32_e32 v167, v68, v68
	v_fmac_f32_e32 v169, v70, v70
	v_add_f32_e32 v167, v167, v169
	v_add_f32_e32 v165, v165, v167
	v_mul_f32_e32 v167, v73, v73
	v_mul_f32_e32 v169, v75, v75
	v_fmac_f32_e32 v167, v72, v72
	v_fmac_f32_e32 v169, v74, v74
	v_add_f32_e32 v167, v167, v169
	v_add_f32_e32 v165, v165, v167
	v_cvt_pk_bf16_f32 v192, v60, v61
	v_cvt_pk_bf16_f32 v193, v62, v63
	v_add_f32_dpp v165, v165, v165 quad_perm:[1,0,3,2] row_mask:0xf bank_mask:0xf
	v_cvt_pk_bf16_f32 v194, v64, v65
	v_cvt_pk_bf16_f32 v195, v66, v67
	v_add_f32_dpp v165, v165, v165 quad_perm:[2,3,0,1] row_mask:0xf bank_mask:0xf
	v_cvt_pk_bf16_f32 v196, v68, v69
	v_cvt_pk_bf16_f32 v197, v70, v71
	v_add_f32_dpp v165, v165, v165 row_half_mirror row_mask:0xf bank_mask:0xf
	v_cvt_pk_bf16_f32 v198, v72, v73
	v_cvt_pk_bf16_f32 v199, v74, v75
	v_add_f32_dpp v165, v165, v165 row_mirror row_mask:0xf bank_mask:0xf
	v_cvt_pk_bf16_f32 v200, v76, v77
	v_cvt_pk_bf16_f32 v201, v78, v79
	v_add_f32_dpp v165, v165, v165 row_bcast:15 row_mask:0xa bank_mask:0xf
	s_nop 1
	v_add_f32_dpp v165, v165, v165 row_bcast:31 row_mask:0xc bank_mask:0xf
	global_store_dwordx2 v161, v[192:193], s[14:15]
	global_store_dwordx2 v161, v[194:195], s[14:15] offset:512
	global_store_dwordx2 v161, v[196:197], s[14:15] offset:1024
	global_store_dwordx2 v161, v[198:199], s[14:15] offset:1536
	global_store_dwordx2 v161, v[200:201], s[16:17]
	s_add_u32 s14, s14, 0x400000
	s_addc_u32 s15, s15, 0
	s_add_u32 s16, s16, 0x100000
	s_addc_u32 s17, s17, 0
	v_fmamk_f32 v177, v165, 0x3a800000, v163
	v_rsq_f32_e32 v177, v177
	s_mov_b64 exec, s[20:21]
	s_nop 0
	global_store_dword v162, v177, s[18:19]
	s_mov_b64 exec, -1
	s_add_u32 s18, s18, 0x2000
	s_addc_u32 s19, s19, 0
	s_branch .LBB0_182

.LBB0_310:
	v_lshl_add_u32 v146, s65, 8, v140
	v_lshl_or_b32 v148, s68, 8, v142
	v_ashrrev_i32_e32 v147, 31, v146
	v_ashrrev_i32_e32 v149, 31, v148
	v_lshlrev_b64 v[150:151], 11, v[146:147]
	v_lshl_add_u64 v[150:151], s[14:15], 0, v[150:151]
	v_lshlrev_b64 v[148:149], 1, v[148:149]
	v_lshl_add_u64 v[150:151], v[150:151], 0, v[148:149]
	v_cvt_pk_bf16_f32 v120, v120, v121
	v_cvt_pk_bf16_f32 v121, v122, v123
	v_cvt_pk_bf16_f32 v122, v124, v125
	v_cvt_pk_bf16_f32 v123, v126, v127
	s_nop 0
	v_readfirstlane_b32 s82, v150
	v_readfirstlane_b32 s83, v151
	ds_write_b128 v230, v[120:123]
	ds_read_b128 v[236:239], v231
	s_nop 1
	s_waitcnt lgkmcnt(0)
	global_store_dwordx4 v233, v[236:239], s[82:83] nt
	v_cvt_pk_bf16_f32 v116, v116, v117
	v_cvt_pk_bf16_f32 v117, v118, v119
	v_cvt_pk_bf16_f32 v118, v112, v113
	v_or_b32_e32 v112, 16, v146
	v_ashrrev_i32_e32 v113, 31, v112
	v_lshlrev_b64 v[112:113], 11, v[112:113]
	v_lshl_add_u64 v[112:113], s[14:15], 0, v[112:113]
	v_lshl_add_u64 v[112:113], v[112:113], 0, v[148:149]
	v_cvt_pk_bf16_f32 v119, v114, v115
	s_nop 0
	v_readfirstlane_b32 s84, v150
	v_readfirstlane_b32 s85, v151
	ds_write_b128 v230, v[116:119]
	ds_read_b128 v[240:243], v231
	s_nop 1
	s_waitcnt lgkmcnt(0)
	global_store_dwordx4 v233, v[240:243], s[84:85] offset:256 nt
	v_cvt_pk_bf16_f32 v108, v108, v109
	v_cvt_pk_bf16_f32 v109, v110, v111
	v_cvt_pk_bf16_f32 v110, v104, v105
	v_cvt_pk_bf16_f32 v111, v106, v107
	s_nop 0
	v_readfirstlane_b32 s82, v112
	v_readfirstlane_b32 s83, v113
	ds_write_b128 v230, v[108:111]
	ds_read_b128 v[236:239], v231
	s_nop 1
	s_waitcnt lgkmcnt(0)
	global_store_dwordx4 v233, v[236:239], s[82:83] nt
	v_cvt_pk_bf16_f32 v100, v100, v101
	v_cvt_pk_bf16_f32 v101, v102, v103
	v_cvt_pk_bf16_f32 v102, v96, v97
	v_or_b32_e32 v96, 32, v146
	v_ashrrev_i32_e32 v97, 31, v96
	v_lshlrev_b64 v[96:97], 11, v[96:97]
	v_lshl_add_u64 v[96:97], s[14:15], 0, v[96:97]
	v_lshl_add_u64 v[96:97], v[96:97], 0, v[148:149]
	v_cvt_pk_bf16_f32 v103, v98, v99
	s_nop 0
	v_readfirstlane_b32 s84, v112
	v_readfirstlane_b32 s85, v113
	ds_write_b128 v230, v[100:103]
	ds_read_b128 v[240:243], v231
	s_nop 1
	s_waitcnt lgkmcnt(0)
	global_store_dwordx4 v233, v[240:243], s[84:85] offset:256 nt
	v_cvt_pk_bf16_f32 v92, v92, v93
	v_cvt_pk_bf16_f32 v93, v94, v95
	v_cvt_pk_bf16_f32 v94, v88, v89
	v_cvt_pk_bf16_f32 v95, v90, v91
	s_nop 0
	v_readfirstlane_b32 s82, v96
	v_readfirstlane_b32 s83, v97
	ds_write_b128 v230, v[92:95]
	ds_read_b128 v[236:239], v231
	s_nop 1
	s_waitcnt lgkmcnt(0)
	global_store_dwordx4 v233, v[236:239], s[82:83] nt
	v_cvt_pk_bf16_f32 v84, v84, v85
	v_cvt_pk_bf16_f32 v85, v86, v87
	v_cvt_pk_bf16_f32 v86, v80, v81
	v_or_b32_e32 v80, 48, v146
	v_ashrrev_i32_e32 v81, 31, v80
	v_lshlrev_b64 v[80:81], 11, v[80:81]
	v_lshl_add_u64 v[80:81], s[14:15], 0, v[80:81]
	v_lshl_add_u64 v[80:81], v[80:81], 0, v[148:149]
	v_cvt_pk_bf16_f32 v87, v82, v83
	s_nop 0
	v_readfirstlane_b32 s84, v96
	v_readfirstlane_b32 s85, v97
	ds_write_b128 v230, v[84:87]
	ds_read_b128 v[240:243], v231
	s_nop 1
	s_waitcnt lgkmcnt(0)
	global_store_dwordx4 v233, v[240:243], s[84:85] offset:256 nt
	v_cvt_pk_bf16_f32 v76, v76, v77
	v_cvt_pk_bf16_f32 v77, v78, v79
	v_cvt_pk_bf16_f32 v78, v72, v73
	v_cvt_pk_bf16_f32 v79, v74, v75
	s_nop 0
	v_readfirstlane_b32 s82, v80
	v_readfirstlane_b32 s83, v81
	ds_write_b128 v230, v[76:79]
	ds_read_b128 v[236:239], v231
	s_nop 1
	s_waitcnt lgkmcnt(0)
	global_store_dwordx4 v233, v[236:239], s[82:83] nt
	v_cvt_pk_bf16_f32 v68, v68, v69
	v_cvt_pk_bf16_f32 v69, v70, v71
	v_cvt_pk_bf16_f32 v70, v64, v65
	v_cvt_pk_bf16_f32 v71, v66, v67
	s_nop 0
	v_readfirstlane_b32 s84, v80
	v_readfirstlane_b32 s85, v81
	ds_write_b128 v230, v[68:71]
	ds_read_b128 v[240:243], v231
	s_nop 1
	s_waitcnt lgkmcnt(0)
	global_store_dwordx4 v233, v[240:243], s[84:85] offset:256 nt
	v_cvt_pk_bf16_f32 v60, v60, v61
	v_cvt_pk_bf16_f32 v61, v62, v63
	v_cvt_pk_bf16_f32 v62, v56, v57
	v_add_co_u32_e32 v56, vcc, s62, v150
	v_lshl_add_u64 v[64:65], v[150:151], 0, s[22:23]
	s_nop 0
	v_addc_co_u32_e32 v57, vcc, 0, v151, vcc
	v_cvt_pk_bf16_f32 v63, v58, v59
	s_nop 0
	v_readfirstlane_b32 s82, v56
	v_readfirstlane_b32 s83, v57
	ds_write_b128 v230, v[60:63]
	ds_read_b128 v[236:239], v231
	s_nop 1
	s_waitcnt lgkmcnt(0)
	global_store_dwordx4 v233, v[236:239], s[82:83] nt
	v_cvt_pk_bf16_f32 v52, v52, v53
	v_cvt_pk_bf16_f32 v53, v54, v55
	v_cvt_pk_bf16_f32 v54, v48, v49
	v_cvt_pk_bf16_f32 v55, v50, v51
	s_nop 0
	v_readfirstlane_b32 s84, v64
	v_readfirstlane_b32 s85, v65
	ds_write_b128 v230, v[52:55]
	ds_read_b128 v[240:243], v231
	s_nop 1
	s_waitcnt lgkmcnt(0)
	global_store_dwordx4 v233, v[240:243], s[84:85] offset:256 nt
	v_cvt_pk_bf16_f32 v44, v44, v45
	v_cvt_pk_bf16_f32 v45, v46, v47
	v_cvt_pk_bf16_f32 v46, v40, v41
	v_add_co_u32_e32 v40, vcc, s63, v150
	v_lshl_add_u64 v[48:49], v[150:151], 0, s[24:25]
	s_nop 0
	v_addc_co_u32_e32 v41, vcc, 0, v151, vcc
	v_cvt_pk_bf16_f32 v47, v42, v43
	s_nop 0
	v_readfirstlane_b32 s82, v40
	v_readfirstlane_b32 s83, v41
	ds_write_b128 v230, v[44:47]
	ds_read_b128 v[236:239], v231
	s_nop 1
	s_waitcnt lgkmcnt(0)
	global_store_dwordx4 v233, v[236:239], s[82:83] nt
	v_cvt_pk_bf16_f32 v36, v36, v37
	v_cvt_pk_bf16_f32 v37, v38, v39
	v_cvt_pk_bf16_f32 v38, v32, v33
	v_cvt_pk_bf16_f32 v39, v34, v35
	s_nop 0
	v_readfirstlane_b32 s84, v48
	v_readfirstlane_b32 s85, v49
	ds_write_b128 v230, v[36:39]
	ds_read_b128 v[240:243], v231
	s_nop 1
	s_waitcnt lgkmcnt(0)
	global_store_dwordx4 v233, v[240:243], s[84:85] offset:256 nt
	v_cvt_pk_bf16_f32 v28, v28, v29
	v_cvt_pk_bf16_f32 v29, v30, v31
	v_cvt_pk_bf16_f32 v30, v24, v25
	v_add_co_u32_e32 v24, vcc, s64, v150
	v_lshl_add_u64 v[32:33], v[150:151], 0, s[36:37]
	s_nop 0
	v_addc_co_u32_e32 v25, vcc, 0, v151, vcc
	v_cvt_pk_bf16_f32 v31, v26, v27
	s_nop 0
	v_readfirstlane_b32 s82, v24
	v_readfirstlane_b32 s83, v25
	ds_write_b128 v230, v[28:31]
	ds_read_b128 v[236:239], v231
	s_nop 1
	s_waitcnt lgkmcnt(0)
	global_store_dwordx4 v233, v[236:239], s[82:83] nt
	v_cvt_pk_bf16_f32 v20, v20, v21
	v_cvt_pk_bf16_f32 v21, v22, v23
	v_cvt_pk_bf16_f32 v22, v16, v17
	v_cvt_pk_bf16_f32 v23, v18, v19
	s_nop 0
	v_readfirstlane_b32 s84, v32
	v_readfirstlane_b32 s85, v33
	ds_write_b128 v230, v[20:23]
	ds_read_b128 v[240:243], v231
	s_nop 1
	s_waitcnt lgkmcnt(0)
	global_store_dwordx4 v233, v[240:243], s[84:85] offset:256 nt
	v_cvt_pk_bf16_f32 v12, v12, v13
	v_cvt_pk_bf16_f32 v13, v14, v15
	v_cvt_pk_bf16_f32 v14, v8, v9
	v_add_co_u32_e32 v8, vcc, 0x58000, v150
	v_lshl_add_u64 v[16:17], v[150:151], 0, s[38:39]
	s_nop 0
	v_addc_co_u32_e32 v9, vcc, 0, v151, vcc
	s_and_b64 vcc, exec, s[4:5]
	s_mov_b64 s[4:5], -1
	v_cvt_pk_bf16_f32 v15, v10, v11
	s_nop 0
	v_readfirstlane_b32 s82, v8
	v_readfirstlane_b32 s83, v9
	ds_write_b128 v230, v[12:15]
	ds_read_b128 v[236:239], v231
	s_nop 1
	s_waitcnt lgkmcnt(0)
	global_store_dwordx4 v233, v[236:239], s[82:83] nt
	v_cvt_pk_bf16_f32 v4, v4, v5
	v_cvt_pk_bf16_f32 v5, v6, v7
	v_cvt_pk_bf16_f32 v6, v0, v1
	v_cvt_pk_bf16_f32 v7, v2, v3
	s_nop 0
	v_readfirstlane_b32 s84, v16
	v_readfirstlane_b32 s85, v17
	ds_write_b128 v230, v[4:7]
	ds_read_b128 v[240:243], v231
	s_nop 1
	s_waitcnt lgkmcnt(0)
	global_store_dwordx4 v233, v[240:243], s[84:85] offset:256 nt
	s_cbranch_vccnz .LBB0_293
	s_andn2_b64 vcc, exec, s[12:13]
	s_cbranch_vccnz .LBB0_292
	s_barrier
	s_branch .LBB0_292
